# chunk scan: direct fragments 2..7, LDS fragments 0,1 read with the first group; all S-operand LDS reads issued before / early in the MFMA chain
# speedup vs baseline: 1.0125x; 1.0005x over previous
; #define LAS __attribute__((address_space(3)))
; __device__ __forceinline__ void dn_scan(const Args& a, LAS unsigned char* lds, int wg, int tid, int wave, int lane) {
;     ...
;     for (int u = tid; u < 2 * 8192 / 4; u += NTHR) ((LAS unsigned*)lds)[u] = 0u;
;     if (wave < 4) {
;         f32x16 acc = zero16();
;         ScanB p0, p1, p2, p3, p4, p5, p6, p7;
;         scanb_load(p0, ws, bh, 0, td, te, lane); scanb_load(p1, ws, bh, 1, td, te, lane); scanb_load(p2, ws, bh, 2, td, te, lane); scanb_load(p3, ws, bh, 3, td, te, lane);
;         scanb_load(p4, ws, bh, 4, td, te, lane); scanb_load(p5, ws, bh, 5, td, te, lane); scanb_load(p6, ws, bh, 6, td, te, lane);
;         WG_BAR();
; #pragma unroll 1
;         for (int n = 0; n < NCH; n += 8) {
;             scanb_load(p7, ws, bh, n + 7, td, te, lane);  scan_step(p0, acc, ws, lds, bh, n, 0, td, te, lane); WG_BAR();
;             scanb_load(p0, ws, bh, n + 8, td, te, lane);  scan_step(p1, acc, ws, lds, bh, n + 1, 1, td, te, lane); WG_BAR();
;             scanb_load(p1, ws, bh, n + 9, td, te, lane);  scan_step(p2, acc, ws, lds, bh, n + 2, 0, td, te, lane); WG_BAR();
;             scanb_load(p2, ws, bh, n + 10, td, te, lane); scan_step(p3, acc, ws, lds, bh, n + 3, 1, td, te, lane); WG_BAR();
;             scanb_load(p3, ws, bh, n + 11, td, te, lane); scan_step(p4, acc, ws, lds, bh, n + 4, 0, td, te, lane); WG_BAR();
;             scanb_load(p4, ws, bh, n + 12, td, te, lane); scan_step(p5, acc, ws, lds, bh, n + 5, 1, td, te, lane); WG_BAR();
;             scanb_load(p5, ws, bh, n + 13, td, te, lane); scan_step(p6, acc, ws, lds, bh, n + 6, 0, td, te, lane); WG_BAR();
;             scanb_load(p6, ws, bh, n + 14, td, te, lane); scan_step(p7, acc, ws, lds, bh, n + 7, 1, td, te, lane); WG_BAR();
;         }
;     } else {
;         ScanA s0, s1, s2, s3;
;         scana_load(s0, ws, bh, 0, td, lane); scana_load(s1, ws, bh, 1, td, lane); scana_load(s2, ws, bh, 2, td, lane);
;         scana_put(s0, lds, 0, td, lane); scana_put(s1, lds, 1, td, lane); scana_put(s2, lds, 2, td, lane);
;         scana_load(s3, ws, bh, 3, td, lane); scana_load(s0, ws, bh, 4, td, lane); scana_load(s1, ws, bh, 5, td, lane); scana_load(s2, ws, bh, 6, td, lane);
;         WG_BAR();
; #pragma unroll 1
;         for (int n = 0; n < NCH; n += 4) {
;             scana_put(s3, lds, n + 3, td, lane); scana_load(s3, ws, bh, n + 7, td, lane); WG_BAR();
.LBB0_1053:
	s_and_b64 vcc, exec, s[4:5]
	s_cbranch_vccz .LBB0_1069
	v_lshrrev_b32_e32 v0, 9, v206
	v_xor_b32_e32 v1, 7, v0
	v_lshl_add_u32 v0, v206, 2, 0
	v_mov_b32_e32 v2, 0
	v_cmp_lt_u32_e32 vcc, 4, v1
	v_cmp_lt_u32_e64 s[4:5], 3, v1
	ds_write2st64_b32 v0, v2, v2 offset1:8
	ds_write2st64_b32 v0, v2, v2 offset0:16 offset1:24
	s_and_saveexec_b64 s[6:7], s[4:5]
	ds_write_b32 v0, v2 offset:8192
	s_or_b64 exec, exec, s[6:7]
	s_and_saveexec_b64 s[4:5], vcc
	v_mov_b32_e32 v2, 0
	ds_write_b32 v0, v2 offset:10240
	s_or_b64 exec, exec, s[4:5]
	v_cmp_lt_u32_e32 vcc, 6, v1
	v_cmp_lt_u32_e64 s[4:5], 5, v1
	s_and_saveexec_b64 s[6:7], s[4:5]
	v_mov_b32_e32 v1, 0
	ds_write_b32 v0, v1 offset:12288
	s_or_b64 exec, exec, s[6:7]
	s_and_saveexec_b64 s[4:5], vcc
	v_mov_b32_e32 v1, 0
	ds_write_b32 v0, v1 offset:14336
	s_or_b64 exec, exec, s[4:5]
	s_mov_b64 s[4:5], -1
	s_cmpk_gt_u32 s70, 0xff
	v_lshlrev_b32_e32 v128, 4, v200
	s_cbranch_scc0 .LBB0_1066
	s_add_u32 s10, s92, 0x2c00000
	s_addc_u32 s11, s93, 0
	s_lshl_b32 s4, s2, 5
	s_and_b32 s4, s4, 0x80
	s_lshl_b32 s6, s2, 15
	s_lshl_b32 s5, s4, 17
	s_and_b32 s6, s6, 0x18000
	s_or_b32 s5, s5, s6
	s_add_u32 s5, s10, s5
	s_addc_u32 s7, s11, 0
	s_lshl_b32 s8, s70, 7
	s_and_b32 s12, s8, 0x6000
	s_add_u32 s8, s5, s12
	s_addc_u32 s9, s7, 0
	v_mov_b32_e32 v129, 0
	v_lshl_add_u64 v[56:57], s[8:9], 0, v[128:129]
	s_movk_i32 s7, 0x1000
	v_add_co_u32_e32 v0, vcc, s7, v56
	s_mov_b32 s5, 0x21000
	s_nop 0
	v_addc_co_u32_e32 v1, vcc, 0, v57, vcc
	v_add_co_u32_e32 v2, vcc, s5, v56
	s_mov_b32 s5, 0x41000
	s_nop 0
	v_addc_co_u32_e32 v3, vcc, 0, v57, vcc
	global_load_dwordx4 v[134:137], v128, s[8:9]
	s_waitcnt lgkmcnt(2)
	global_load_dwordx4 v[138:141], v128, s[8:9] offset:1024
	s_mov_b64 s[8:9], 0x20000
	v_add_co_u32_e32 v6, vcc, s5, v56
	v_lshl_add_u64 v[0:1], v[56:57], 0, s[8:9]
	s_mov_b64 s[8:9], 0x40000
	v_addc_co_u32_e32 v7, vcc, 0, v57, vcc
	s_mov_b32 s5, 0x61000
	global_load_dwordx4 v[166:169], v[0:1], off offset:1024
	global_load_dwordx4 v[174:177], v[2:3], off offset:-4096
	v_lshl_add_u64 v[4:5], v[56:57], 0, s[8:9]
	global_load_dwordx4 v[194:197], v[6:7], off offset:-4096
	global_load_dwordx4 v[208:211], v[4:5], off offset:1024
	v_add_co_u32_e32 v0, vcc, s5, v56
	s_mov_b32 s5, 0x81000
	s_nop 0
	v_addc_co_u32_e32 v1, vcc, 0, v57, vcc
	v_add_co_u32_e32 v28, vcc, s5, v56
	s_mov_b64 s[8:9], 0x60000
	s_nop 0
	v_addc_co_u32_e32 v29, vcc, 0, v57, vcc
	s_mov_b32 s5, 0xa1000
	v_lshl_add_u64 v[4:5], v[56:57], 0, s[8:9]
	s_mov_b64 s[8:9], 0x80000
	v_add_co_u32_e32 v58, vcc, s5, v56
	v_lshl_add_u64 v[12:13], v[56:57], 0, s[8:9]
	s_mov_b64 s[8:9], 0xa0000
	v_addc_co_u32_e32 v59, vcc, 0, v57, vcc
	s_mov_b32 s5, 0xc1000
	v_lshl_add_u64 v[64:65], v[56:57], 0, s[8:9]
	s_mov_b64 s[8:9], 0xc0000
	v_add_co_u32_e32 v92, vcc, s5, v56
	v_lshl_add_u64 v[76:77], v[56:57], 0, s[8:9]
	s_nop 0
	v_addc_co_u32_e32 v93, vcc, 0, v57, vcc
	global_load_dwordx4 v[96:99], v[4:5], off offset:1024
	global_load_dwordx4 v[104:107], v[0:1], off offset:-4096
	s_nop 0
	global_load_dwordx4 v[0:3], v[28:29], off offset:-4096
	s_nop 0
	global_load_dwordx4 v[4:7], v[12:13], off offset:1024
	s_nop 0
	s_nop 0
	s_nop 0
	s_nop 0
	global_load_dwordx4 v[32:35], v[64:65], off offset:1024
	global_load_dwordx4 v[40:43], v[58:59], off offset:-4096
	s_nop 0
	s_nop 0
	global_load_dwordx4 v[60:63], v[92:93], off offset:-4096
	s_nop 0
	s_nop 0
	global_load_dwordx4 v[68:71], v[76:77], off offset:1024
	s_nop 0
	s_nop 0
	s_nop 0
	s_add_i32 s8, s12, 0
	s_add_i32 s9, s8, 0x14000
	v_add_u32_e32 v132, s8, v128
	v_add_u32_e32 v133, s9, v128
	s_add_i32 s8, s8, 0x1c000
	s_or_b32 s9, s4, 7
	s_add_u32 s10, s10, s12
	s_addc_u32 s11, s11, 0
	s_mov_b32 s5, 0
	v_lshl_add_u64 v[130:131], s[10:11], 0, v[128:129]
	s_or_b32 s10, s4, 8
	s_or_b32 s11, s4, 9
	s_or_b32 s12, s4, 10
	s_mov_b32 s13, -4
	s_waitcnt vmcnt(13)
	ds_write_b128 v132, v[134:137] offset:16384
	s_waitcnt vmcnt(12)
	ds_write_b128 v132, v[138:141] offset:17408
	s_waitcnt vmcnt(10)
	ds_write_b128 v132, v[174:177] offset:49152
	ds_write_b128 v132, v[166:169] offset:50176
	s_waitcnt vmcnt(9)
	ds_write_b128 v133, v[194:197]
	s_waitcnt vmcnt(8)
	ds_write_b128 v133, v[208:211] offset:1024
	s_waitcnt lgkmcnt(0)
	s_barrier
.LBB0_1064:
	s_add_i32 s13, s13, 4
	s_min_u32 s4, s13, 0x78
	s_add_i32 s4, s9, s4
	s_min_u32 s14, s13, 0x77
	s_lshl_b32 s4, s4, 17
	v_add_u32_e32 v129, s8, v128
	s_add_i32 s14, s10, s14
	s_or_b32 s4, s4, s6
	s_waitcnt vmcnt(6)
	ds_write_b128 v129, v[104:107]
	s_waitcnt vmcnt(6)
	ds_write_b128 v129, v[96:99] offset:1024
	s_min_u32 s15, s13, 0x76
	s_lshl_b32 s14, s14, 17
	v_lshl_add_u64 v[108:109], v[130:131], 0, s[4:5]
	s_add_i32 s15, s11, s15
	s_or_b32 s4, s14, s6
	v_add_co_u32_e32 v124, vcc, s7, v108
	s_lshl_b32 s15, s15, 17
	s_nop 0
	v_addc_co_u32_e32 v125, vcc, 0, v109, vcc
	v_lshl_add_u64 v[134:135], v[130:131], 0, s[4:5]
	global_load_dwordx4 v[104:107], v[108:109], off
	global_load_dwordx4 v[96:99], v[108:109], off offset:1024
	s_or_b32 s4, s15, s6
	s_nop 0
	s_waitcnt lgkmcnt(0)
	s_barrier
	s_waitcnt vmcnt(7)
	ds_write_b128 v132, v[0:3] offset:16384
	s_waitcnt vmcnt(6)
	ds_write_b128 v132, v[4:7] offset:17408
	v_add_co_u32_e32 v28, vcc, s7, v134
	v_lshl_add_u64 v[136:137], v[130:131], 0, s[4:5]
	s_nop 0
	v_addc_co_u32_e32 v29, vcc, 0, v135, vcc
	s_min_u32 s18, s13, 0x75
	global_load_dwordx4 v[0:3], v[134:135], off
	global_load_dwordx4 v[4:7], v[134:135], off offset:1024
	s_nop 0
	s_waitcnt lgkmcnt(0)
	s_barrier
	s_waitcnt vmcnt(6)
	ds_write_b128 v132, v[40:43] offset:49152
	s_waitcnt vmcnt(6)
	ds_write_b128 v132, v[32:35] offset:50176
	v_add_co_u32_e32 v56, vcc, s7, v136
	s_add_i32 s18, s12, s18
	s_nop 0
	v_addc_co_u32_e32 v57, vcc, 0, v137, vcc
	s_lshl_b32 s18, s18, 17
	global_load_dwordx4 v[40:43], v[136:137], off
	global_load_dwordx4 v[32:35], v[136:137], off offset:1024
	s_nop 0
	s_or_b32 s4, s18, s6
	v_lshl_add_u64 v[134:135], v[130:131], 0, s[4:5]
	s_waitcnt lgkmcnt(0)
	s_barrier
	s_waitcnt vmcnt(7)
	ds_write_b128 v133, v[60:63]
	s_waitcnt vmcnt(6)
	ds_write_b128 v133, v[68:71] offset:1024
	v_add_co_u32_e32 v92, vcc, 0x1000, v134
	global_load_dwordx4 v[60:63], v[134:135], off
	global_load_dwordx4 v[68:71], v[134:135], off offset:1024
	v_addc_co_u32_e32 v93, vcc, 0, v135, vcc
	s_nop 0
	s_waitcnt lgkmcnt(0)
	s_barrier
	s_cmpk_gt_u32 s13, 0x7b
	s_cbranch_scc0 .LBB0_1064
	s_mov_b64 s[4:5], 0
; #define WG_BAR() do { asm volatile("s_waitcnt lgkmcnt(0)" ::: "memory"); __builtin_amdgcn_s_barrier(); asm volatile("" ::: "memory"); } while (0)
; __device__ __forceinline__ int scan_item(int bh, int n) { if (n > NCH - 1) n = NCH - 1; return ((bh >> 2) * NCH + n) * 4 + (bh & 3); }
; __device__ __forceinline__ void scana_load(ScanA& p, const unsigned char* ws, int bh, int n, int td, int lane) {
;     const bf16* Ms = (const bf16*)(ws + WS_MS) + (size_t)scan_item(bh, n) * 16384 + td * 4096 + lane * 8;
; #pragma unroll
;     for (int q = 0; q < 8; ++q) p.a[q] = *(const bf16x8*)(Ms + 512 * q);
; __device__ __forceinline__ void dn_scan(const Args& a, LAS unsigned char* lds, int wg, int tid, int wave, int lane) {
;     ...
;     if (wave < 4) {
;         f32x16 acc = zero16();
;         ScanB p0, p1, p2, p3, p4, p5, p6, p7;
;         scanb_load(p0, ws, bh, 0, td, te, lane); scanb_load(p1, ws, bh, 1, td, te, lane); scanb_load(p2, ws, bh, 2, td, te, lane); scanb_load(p3, ws, bh, 3, td, te, lane);
;         scanb_load(p4, ws, bh, 4, td, te, lane); scanb_load(p5, ws, bh, 5, td, te, lane); scanb_load(p6, ws, bh, 6, td, te, lane);
;         WG_BAR();
.LBB0_1066:
	s_and_b64 vcc, exec, s[4:5]
	s_cbranch_vccz .LBB0_1069
	s_lshl_b32 s4, s2, 5
	s_and_b32 s12, s4, 0x80
	s_lshl_b32 s4, s12, 2
	s_and_b32 s13, s2, 3
	s_or_b32 s8, s4, s13
	s_add_u32 s4, s92, 0x1390000
	s_addc_u32 s5, s93, 0
	s_lshl_b32 s6, s8, 2
	s_add_u32 s9, s92, 0xcc00000
	s_waitcnt vmcnt(23)
	v_mov_b32_e32 v0, s6
	s_addc_u32 s10, s93, 0
	s_lshl_b32 s6, s8, 15
	s_add_u32 s6, s9, s6
	s_addc_u32 s7, s10, 0
	s_lshl_b32 s14, s2, 10
	s_lshl_b32 s11, s64, 11
	s_and_b32 s14, s14, 0x6000
	s_or_b32 s11, s11, s14
	s_add_u32 s6, s6, s11
	s_addc_u32 s7, s7, 0
	global_load_dwordx4 v[60:63], v128, s[6:7]
	global_load_dwordx4 v[56:59], v128, s[6:7] offset:1024
	s_or_b32 s6, s8, 4
	s_lshl_b32 s7, s6, 2
	s_lshl_b32 s6, s6, 15
	s_add_u32 s6, s9, s6
	v_mov_b32_e32 v1, s7
	s_addc_u32 s7, s10, 0
	s_add_u32 s6, s6, s11
	s_addc_u32 s7, s7, 0
	global_load_dwordx4 v[76:79], v128, s[6:7]
	global_load_dwordx4 v[68:71], v128, s[6:7] offset:1024
	s_or_b32 s6, s8, 8
	s_lshl_b32 s7, s6, 2
	s_lshl_b32 s6, s6, 15
	s_add_u32 s6, s9, s6
	v_mov_b32_e32 v2, s7
	s_addc_u32 s7, s10, 0
	s_add_u32 s6, s6, s11
	s_addc_u32 s7, s7, 0
	global_load_dwordx4 v[84:87], v128, s[6:7]
	global_load_dwordx4 v[80:83], v128, s[6:7] offset:1024
	s_or_b32 s6, s8, 12
	s_lshl_b32 s7, s6, 2
	s_lshl_b32 s6, s6, 15
	s_add_u32 s6, s9, s6
	v_mov_b32_e32 v3, s7
	s_addc_u32 s7, s10, 0
	s_add_u32 s6, s6, s11
	s_addc_u32 s7, s7, 0
	global_load_dwordx4 v[36:39], v128, s[6:7]
	global_load_dwordx4 v[32:35], v128, s[6:7] offset:1024
	s_or_b32 s6, s8, 16
	s_lshl_b32 s7, s6, 2
	s_lshl_b32 s6, s6, 15
	s_add_u32 s6, s9, s6
	s_waitcnt vmcnt(30)
	v_mov_b32_e32 v4, s7
	s_addc_u32 s7, s10, 0
	s_add_u32 s6, s6, s11
	s_addc_u32 s7, s7, 0
	global_load_dwordx4 v[44:47], v128, s[6:7]
	global_load_dwordx4 v[40:43], v128, s[6:7] offset:1024
	s_or_b32 s6, s8, 20
	s_lshl_b32 s7, s6, 2
	s_lshl_b32 s6, s6, 15
	s_add_u32 s6, s9, s6
	v_mov_b32_e32 v5, s7
	s_addc_u32 s7, s10, 0
	s_add_u32 s6, s6, s11
	s_addc_u32 s7, s7, 0
	global_load_dwordx4 v[52:55], v128, s[6:7]
	global_load_dwordx4 v[48:51], v128, s[6:7] offset:1024
	s_or_b32 s6, s8, 24
	s_lshl_b32 s7, s6, 2
	v_mov_b32_e32 v6, s7
	global_load_dword v126, v0, s[4:5]
	global_load_dword v124, v1, s[4:5]
	global_load_dword v122, v2, s[4:5]
	global_load_dword v114, v3, s[4:5]
	global_load_dword v116, v4, s[4:5]
	global_load_dword v118, v5, s[4:5]
	global_load_dword v120, v6, s[4:5]
	s_lshl_b32 s6, s6, 15
	s_add_u32 s6, s9, s6
	s_addc_u32 s7, s10, 0
	s_add_u32 s6, s6, s11
	s_addc_u32 s7, s7, 0
	global_load_dwordx4 v[72:75], v128, s[6:7]
	global_load_dwordx4 v[64:67], v128, s[6:7] offset:1024
	s_add_u32 s8, s9, s11
	s_addc_u32 s9, s10, 0
	s_lshl_b32 s6, s64, 13
	v_mov_b32_e32 v129, 0
	s_add_i32 s14, s6, 0
	s_mul_i32 s6, s64, 0xffffe800
	v_lshl_add_u64 v[96:97], s[8:9], 0, v[128:129]
	s_add_i32 s15, s14, s6
	s_mul_i32 s9, s64, 0x1800
	s_add_i32 s18, s15, s9
	s_bfe_u32 s9, s2, 0x10002
	s_lshl_b32 s8, s13, 15
	s_add_i32 s19, s18, s6
	s_lshl_b32 s6, s9, 24
	s_or_b32 s8, s6, s8
	s_mov_b32 s7, 0
	v_lshl_or_b32 v0, v200, 4, s11
	v_mov_b32_e32 v1, v129
	s_or_b32 s6, s8, 0xc0000
	v_lshl_add_u64 v[98:99], v[0:1], 0, s[6:7]
	s_or_b32 s6, s8, 0xa0000
	v_lshl_add_u64 v[100:101], v[0:1], 0, s[6:7]
	s_or_b32 s6, s8, 0x80000
	v_lshl_add_u64 v[102:103], v[0:1], 0, s[6:7]
	s_or_b32 s6, s8, 0x60000
	v_lshl_add_u64 v[104:105], v[0:1], 0, s[6:7]
	s_or_b32 s6, s8, 0x40000
	v_lshl_add_u64 v[106:107], v[0:1], 0, s[6:7]
	s_or_b32 s6, s8, 0x20000
	v_lshl_add_u64 v[108:109], v[0:1], 0, s[6:7]
	s_lshl_b32 s6, s9, 9
	s_or_b32 s6, s6, s13
	s_or_b32 s9, s6, 28
	s_waitcnt lgkmcnt(0)
	s_barrier
	s_lshl_b32 s6, s9, 2
	s_or_b32 s6, s6, 0x1390000
	s_lshl_b32 s10, s9, 15
	s_mov_b32 s11, s7
	s_mov_b32 s9, s7
	s_or_b32 s20, s12, 9
	s_add_i32 s21, s14, 0x14000
	s_or_b32 s22, s12, 10
	s_add_i32 s23, s14, 0x1c000
	s_or_b32 s24, s12, 11
	s_or_b32 s25, s12, 12
	s_or_b32 s26, s12, 13
	s_or_b32 s27, s12, 14
	v_lshl_add_u64 v[110:111], v[0:1], 0, s[10:11]
	v_lshl_add_u64 v[112:113], v[0:1], 0, s[8:9]
	s_mov_b32 s30, -8
	s_mov_b32 s28, 0xcc00000
	s_mov_b64 s[8:9], 0x100000
	s_mov_b64 s[10:11], s[6:7]
	v_mov_b32_e32 v0, 0
	v_mov_b32_e32 v2, 0
	v_mov_b32_e32 v3, v129
	v_mov_b32_e32 v4, 0
	v_mov_b32_e32 v5, v129
	v_mov_b32_e32 v6, 0
	v_mov_b32_e32 v7, v129
	s_waitcnt vmcnt(42)
	v_mov_b32_e32 v8, 0
	v_mov_b32_e32 v9, v129
	v_mov_b32_e32 v10, 0
	v_mov_b32_e32 v11, v129
	s_waitcnt vmcnt(41)
	v_mov_b32_e32 v12, 0
	v_mov_b32_e32 v13, v129
	v_mov_b32_e32 v14, 0
	v_mov_b32_e32 v15, v129
	s_bfe_u32 s98, s2, 0x10002
	s_lshl_b32 s98, s98, 24
	s_and_b32 s100, s2, 3
	s_lshl_b32 s100, s100, 15
	s_or_b32 s98, s98, s100
	s_lshl_b32 s100, s64, 13
	s_or_b32 s98, s98, s100
	s_add_u32 s98, s98, 0x2c00000
	s_add_u32 s100, s92, s98
	s_addc_u32 s101, s93, 0
	v_add_u32_e32 v147, 0x1000, v128
	global_load_dwordx4 v[148:151], v128, s[100:101] offset:2048
	global_load_dwordx4 v[152:155], v128, s[100:101] offset:3072
	global_load_dwordx4 v[156:159], v147, s[100:101]
	global_load_dwordx4 v[160:163], v147, s[100:101] offset:1024
	global_load_dwordx4 v[164:167], v147, s[100:101] offset:2048
	global_load_dwordx4 v[168:171], v147, s[100:101] offset:3072
	v_add_u32_e32 v146, 0x20000, v128
	v_add_u32_e32 v147, 0x21000, v128
	global_load_dwordx4 v[172:175], v146, s[100:101] offset:2048
	global_load_dwordx4 v[176:179], v146, s[100:101] offset:3072
	global_load_dwordx4 v[180:183], v147, s[100:101]
	global_load_dwordx4 v[184:187], v147, s[100:101] offset:1024
	global_load_dwordx4 v[188:191], v147, s[100:101] offset:2048
	global_load_dwordx4 v[192:195], v147, s[100:101] offset:3072
	v_add_u32_e32 v146, 0x40000, v128
	v_add_u32_e32 v147, 0x41000, v128
	global_load_dwordx4 v[196:199], v146, s[100:101] offset:2048
	global_load_dwordx4 v[208:211], v146, s[100:101] offset:3072
	global_load_dwordx4 v[212:215], v147, s[100:101]
	global_load_dwordx4 v[216:219], v147, s[100:101] offset:1024
	global_load_dwordx4 v[220:223], v147, s[100:101] offset:2048
	global_load_dwordx4 v[224:227], v147, s[100:101] offset:3072
	v_add_u32_e32 v146, 0x60000, v128
	v_add_u32_e32 v147, 0x61000, v128
	global_load_dwordx4 v[228:231], v146, s[100:101] offset:2048
	global_load_dwordx4 v[232:235], v146, s[100:101] offset:3072
	global_load_dwordx4 v[236:239], v147, s[100:101]
	global_load_dwordx4 v[240:243], v147, s[100:101] offset:1024
	global_load_dwordx4 v[244:247], v147, s[100:101] offset:2048
	global_load_dwordx4 v[248:251], v147, s[100:101] offset:3072
	s_waitcnt vmcnt(0)
; __device__ __forceinline__ void scan_step(const ScanB& p, f32x16& acc, unsigned char* ws, LAS unsigned char* lds, int bh, int n, int cur, int td, int te, int lane) {
;     const int item = scan_item(bh, n);
;     v4u b0 = p.bn[0], b1 = p.bn[1]; float egl = p.egl;
;     asm volatile("" : "+v"(egl)); asm volatile("" : "+v"(b0)); asm volatile("" : "+v"(b1));
;     f32x16 bv16; ans_unpack(b0, b1, bv16);
; #pragma unroll
;     for (int r = 0; r < 16; ++r) acc[r] = acc[r] * egl + bv16[r];
;     const LAS unsigned char* sb = lds + cur * 8192 + lane * 16;
;     const LAS unsigned char* sa = lds + SC_RING + (n & 3) * SC_SLOT + td * 8192 + lane * 16;
;     f32x16 acc2 = zero16();
; #pragma unroll
;     for (int q = 0; q < 8; q += 2) {
;         const bf16x8 a0 = *(const LAS bf16x8*)(sa + 1024 * q), bv0 = *(const LAS bf16x8*)(sb + 1024 * q);
;         const bf16x8 a1 = *(const LAS bf16x8*)(sa + 1024 * (q + 1)), bv1 = *(const LAS bf16x8*)(sb + 1024 * (q + 1));
;         acc = __builtin_amdgcn_mfma_f32_32x32x16_bf16(a0, bv0, acc, 0, 0, 0); acc2 = __builtin_amdgcn_mfma_f32_32x32x16_bf16(a1, bv1, acc2, 0, 0, 0); }
; #pragma unroll
;     for (int r = 0; r < 16; ++r) acc[r] += acc2[r];
;     v4u w0, w1; ans_pack(acc, w0, w1);
;     LAS unsigned char* sn = lds + (cur ^ 1) * 8192 + td * 2048 + lane * 16;
;     *(LAS v4u*)sn = w0; *(LAS v4u*)(sn + 1024) = w1;
;     bf16* So = (bf16*)(ws + WS_BS) + (size_t)item * 16384 + (te * 4 + td) * 1024 + lane * 8;
;     *(v4u*)So = w0; *(v4u*)(So + 512) = w1;
; __device__ __forceinline__ void dn_scan(const Args& a, LAS unsigned char* lds, int wg, int tid, int wave, int lane) {
;     ...
;             scanb_load(p7, ws, bh, n + 7, td, te, lane);  scan_step(p0, acc, ws, lds, bh, n, 0, td, te, lane); WG_BAR();
;             scanb_load(p0, ws, bh, n + 8, td, te, lane);  scan_step(p1, acc, ws, lds, bh, n + 1, 1, td, te, lane); WG_BAR();
;             scanb_load(p1, ws, bh, n + 9, td, te, lane);  scan_step(p2, acc, ws, lds, bh, n + 2, 0, td, te, lane); WG_BAR();
;             scanb_load(p2, ws, bh, n + 10, td, te, lane); scan_step(p3, acc, ws, lds, bh, n + 3, 1, td, te, lane); WG_BAR();
;             scanb_load(p3, ws, bh, n + 11, td, te, lane); scan_step(p4, acc, ws, lds, bh, n + 4, 0, td, te, lane); WG_BAR();
;             scanb_load(p4, ws, bh, n + 12, td, te, lane); scan_step(p5, acc, ws, lds, bh, n + 5, 1, td, te, lane); WG_BAR();
.LBB0_1068:
	v_lshl_add_u64 v[16:17], s[92:93], 0, v[110:111]
	s_add_i32 s29, s30, 8
	v_mov_b32_e32 v201, s29
	v_add_co_u32_e32 v130, vcc, s28, v16
	v_add_u32_e32 v123, s14, v128
	s_add_u32 s34, s92, s10
	v_addc_co_u32_e32 v131, vcc, 0, v17, vcc
	v_add_u32_e32 v115, 0, v128
	s_addc_u32 s35, s93, s11
	global_load_dwordx4 v[92:95], v[130:131], off
	global_load_dwordx4 v[88:91], v[130:131], off offset:1024
	global_load_dword v132, v129, s[34:35]
	ds_read_b128 v[16:19], v123 offset:16384
	ds_read_b128 v[20:23], v123 offset:17408
	ds_read_b128 v[24:27], v115
	ds_read_b128 v[28:31], v115 offset:1024
	v_lshlrev_b32_e32 v134, 16, v60
	v_and_b32_e32 v135, 0xffff0000, v60
	v_lshlrev_b32_e32 v60, 16, v61
	v_and_b32_e32 v61, 0xffff0000, v61
	v_lshlrev_b32_e32 v136, 16, v62
	v_and_b32_e32 v137, 0xffff0000, v62
	v_lshlrev_b32_e32 v62, 16, v63
	v_and_b32_e32 v63, 0xffff0000, v63
	v_lshlrev_b32_e32 v138, 16, v56
	v_and_b32_e32 v139, 0xffff0000, v56
	v_lshlrev_b32_e32 v56, 16, v57
	v_and_b32_e32 v57, 0xffff0000, v57
	v_lshlrev_b32_e32 v140, 16, v58
	v_and_b32_e32 v141, 0xffff0000, v58
	v_lshlrev_b32_e32 v58, 16, v59
	v_and_b32_e32 v59, 0xffff0000, v59
	v_pk_fma_f32 v[0:1], v[0:1], v[126:127], v[134:135] op_sel_hi:[1,0,1]
	v_pk_fma_f32 v[2:3], v[2:3], v[126:127], v[60:61] op_sel_hi:[1,0,1]
	v_pk_fma_f32 v[4:5], v[4:5], v[126:127], v[136:137] op_sel_hi:[1,0,1]
	v_pk_fma_f32 v[6:7], v[6:7], v[126:127], v[62:63] op_sel_hi:[1,0,1]
	v_pk_fma_f32 v[8:9], v[8:9], v[126:127], v[138:139] op_sel_hi:[1,0,1]
	v_pk_fma_f32 v[10:11], v[10:11], v[126:127], v[56:57] op_sel_hi:[1,0,1]
	v_pk_fma_f32 v[12:13], v[12:13], v[126:127], v[140:141] op_sel_hi:[1,0,1]
	v_pk_fma_f32 v[14:15], v[14:15], v[126:127], v[58:59] op_sel_hi:[1,0,1]
	ds_read_b128 v[60:63], v115 offset:2048
	ds_read_b128 v[138:141], v115 offset:3072
	ds_read_b128 v[252:255], v115 offset:4096
	ds_read_b128 v[202:205], v115 offset:5120
	s_waitcnt lgkmcnt(5)
	v_mfma_f32_32x32x16_bf16 v[0:15], v[16:19], v[24:27], v[0:15]
	s_add_i32 s6, s30, 16
	s_min_u32 s6, s6, 0x7f
	s_or_b32 s6, s6, s12
	s_lshl_b32 s6, s6, 2
	v_add_u32_e32 v117, s15, v128
	s_or_b32 s6, s6, s13
	s_lshl_b32 s30, s6, 2
	s_waitcnt lgkmcnt(4)
	v_mfma_f32_32x32x16_bf16 v[16:31], v[20:23], v[28:31], 0
	v_add_u32_e32 v121, s18, v128
	s_lshl_b32 s6, s6, 15
	v_lshl_add_u64 v[142:143], v[96:97], 0, s[6:7]
	s_min_u32 s6, s29, 0x76
	s_add_i32 s6, s20, s6
	s_lshl_b32 s6, s6, 2
	v_add_u32_e32 v119, s19, v128
	v_add_u32_e32 v146, 4, v201
	v_min_u32_e32 v146, 0x7f, v146
	v_lshl_add_u32 v146, v146, 17, v128
	v_add_u32_e32 v147, 0x1000, v146
	s_waitcnt vmcnt(43)
	s_waitcnt lgkmcnt(3)
	v_mfma_f32_32x32x16_bf16 v[0:15], v[148:151], v[60:63], v[0:15]
	global_load_dwordx4 v[148:151], v146, s[100:101] offset:2048
	s_or_b32 s6, s6, s13
	v_lshl_add_u64 v[110:111], v[110:111], 0, s[8:9]
	s_waitcnt vmcnt(43)
	s_waitcnt lgkmcnt(2)
	v_mfma_f32_32x32x16_bf16 v[16:31], v[152:155], v[138:141], v[16:31]
	global_load_dwordx4 v[152:155], v146, s[100:101] offset:3072
	ds_read_b128 v[60:63], v115 offset:6144
	ds_read_b128 v[138:141], v115 offset:7168
	s_waitcnt vmcnt(43)
	s_waitcnt lgkmcnt(3)
	v_mfma_f32_32x32x16_bf16 v[0:15], v[156:159], v[252:255], v[0:15]
	global_load_dwordx4 v[156:159], v147, s[100:101]
	v_lshl_add_u64 v[56:57], s[92:93], 0, v[112:113]
	v_add_co_u32_e32 v126, vcc, s28, v56
	v_lshl_add_u64 v[112:113], v[112:113], 0, s[8:9]
	s_nop 0
	v_addc_co_u32_e32 v127, vcc, 0, v57, vcc
	s_waitcnt vmcnt(43)
	s_waitcnt lgkmcnt(2)
	v_mfma_f32_32x32x16_bf16 v[16:31], v[160:163], v[202:205], v[16:31]
	global_load_dwordx4 v[160:163], v147, s[100:101] offset:1024
	s_waitcnt vmcnt(43)
	s_waitcnt lgkmcnt(1)
	v_mfma_f32_32x32x16_bf16 v[0:15], v[164:167], v[60:63], v[0:15]
	global_load_dwordx4 v[164:167], v147, s[100:101] offset:2048
	v_mov_b32_e32 v56, s30
	s_lshl_b32 s30, s6, 2
	s_lshl_b32 s6, s6, 15
	v_lshl_add_u64 v[144:145], v[96:97], 0, s[6:7]
	s_min_u32 s6, s29, 0x75
	s_add_i32 s6, s22, s6
	s_lshl_b32 s6, s6, 2
	s_waitcnt vmcnt(43)
	s_waitcnt lgkmcnt(0)
	v_mfma_f32_32x32x16_bf16 v[16:31], v[168:171], v[138:141], v[16:31]
	global_load_dwordx4 v[168:171], v147, s[100:101] offset:3072
	s_or_b32 s6, s6, s13
	s_nop 10
	v_pk_add_f32 v[134:135], v[6:7], v[22:23]
	v_pk_add_f32 v[136:137], v[4:5], v[20:21]
	v_pk_add_f32 v[138:139], v[2:3], v[18:19]
	v_pk_add_f32 v[140:141], v[0:1], v[16:17]
	v_pk_add_f32 v[14:15], v[14:15], v[30:31]
	v_pk_add_f32 v[12:13], v[12:13], v[28:29]
	v_pk_add_f32 v[10:11], v[10:11], v[26:27]
	v_pk_add_f32 v[8:9], v[8:9], v[24:25]
	v_cvt_pk_bf16_f32 v0, v140, v141
	v_cvt_pk_bf16_f32 v1, v138, v139
	v_cvt_pk_bf16_f32 v2, v136, v137
	v_cvt_pk_bf16_f32 v3, v134, v135
	v_cvt_pk_bf16_f32 v4, v8, v9
	v_cvt_pk_bf16_f32 v5, v10, v11
	v_cvt_pk_bf16_f32 v6, v12, v13
	v_cvt_pk_bf16_f32 v7, v14, v15
	ds_write_b128 v117, v[0:3] offset:8192
	ds_write_b128 v117, v[4:7] offset:9216
	global_store_dwordx4 v[126:127], v[0:3], off
	global_store_dwordx4 v[126:127], v[4:7], off offset:1024
	s_waitcnt lgkmcnt(0)
	s_barrier
; __device__ __forceinline__ void scan_step(const ScanB& p, f32x16& acc, unsigned char* ws, LAS unsigned char* lds, int bh, int n, int cur, int td, int te, int lane) {
;     const int item = scan_item(bh, n);
;     v4u b0 = p.bn[0], b1 = p.bn[1]; float egl = p.egl;
;     asm volatile("" : "+v"(egl)); asm volatile("" : "+v"(b0)); asm volatile("" : "+v"(b1));
;     f32x16 bv16; ans_unpack(b0, b1, bv16);
; #pragma unroll
;     for (int r = 0; r < 16; ++r) acc[r] = acc[r] * egl + bv16[r];
;     const LAS unsigned char* sb = lds + cur * 8192 + lane * 16;
;     const LAS unsigned char* sa = lds + SC_RING + (n & 3) * SC_SLOT + td * 8192 + lane * 16;
;     f32x16 acc2 = zero16();
; #pragma unroll
;     for (int q = 0; q < 8; q += 2) {
;         const bf16x8 a0 = *(const LAS bf16x8*)(sa + 1024 * q), bv0 = *(const LAS bf16x8*)(sb + 1024 * q);
;         const bf16x8 a1 = *(const LAS bf16x8*)(sa + 1024 * (q + 1)), bv1 = *(const LAS bf16x8*)(sb + 1024 * (q + 1));
;         acc = __builtin_amdgcn_mfma_f32_32x32x16_bf16(a0, bv0, acc, 0, 0, 0); acc2 = __builtin_amdgcn_mfma_f32_32x32x16_bf16(a1, bv1, acc2, 0, 0, 0); }
; #pragma unroll
;     for (int r = 0; r < 16; ++r) acc[r] += acc2[r];
;     v4u w0, w1; ans_pack(acc, w0, w1);
;     LAS unsigned char* sn = lds + (cur ^ 1) * 8192 + td * 2048 + lane * 16;
;     *(LAS v4u*)sn = w0; *(LAS v4u*)(sn + 1024) = w1;
;     bf16* So = (bf16*)(ws + WS_BS) + (size_t)item * 16384 + (te * 4 + td) * 1024 + lane * 8;
;     *(v4u*)So = w0; *(v4u*)(So + 512) = w1;
; __device__ __forceinline__ void dn_scan(const Args& a, LAS unsigned char* lds, int wg, int tid, int wave, int lane) {
;     ...
;             scanb_load(p7, ws, bh, n + 7, td, te, lane);  scan_step(p0, acc, ws, lds, bh, n, 0, td, te, lane); WG_BAR();
;             scanb_load(p0, ws, bh, n + 8, td, te, lane);  scan_step(p1, acc, ws, lds, bh, n + 1, 1, td, te, lane); WG_BAR();
;             scanb_load(p1, ws, bh, n + 9, td, te, lane);  scan_step(p2, acc, ws, lds, bh, n + 2, 0, td, te, lane); WG_BAR();
;             scanb_load(p2, ws, bh, n + 10, td, te, lane); scan_step(p3, acc, ws, lds, bh, n + 3, 1, td, te, lane); WG_BAR();
;             scanb_load(p3, ws, bh, n + 11, td, te, lane); scan_step(p4, acc, ws, lds, bh, n + 4, 0, td, te, lane); WG_BAR();
;             scanb_load(p4, ws, bh, n + 12, td, te, lane); scan_step(p5, acc, ws, lds, bh, n + 5, 1, td, te, lane); WG_BAR();
	global_load_dword v126, v56, s[4:5]
	global_load_dwordx4 v[60:63], v[142:143], off
	s_nop 0
	global_load_dwordx4 v[56:59], v[142:143], off offset:1024
	ds_read_b128 v[16:19], v121 offset:49152
	ds_read_b128 v[20:23], v121 offset:50176
	ds_read_b128 v[24:27], v115 offset:8192
	ds_read_b128 v[28:31], v115 offset:9216
	v_lshlrev_b32_e32 v0, 16, v76
	v_and_b32_e32 v1, 0xffff0000, v76
	v_lshlrev_b32_e32 v2, 16, v77
	v_and_b32_e32 v3, 0xffff0000, v77
	v_lshlrev_b32_e32 v4, 16, v78
	v_and_b32_e32 v5, 0xffff0000, v78
	v_lshlrev_b32_e32 v6, 16, v79
	v_and_b32_e32 v7, 0xffff0000, v79
	v_lshlrev_b32_e32 v76, 16, v68
	v_and_b32_e32 v77, 0xffff0000, v68
	v_lshlrev_b32_e32 v68, 16, v69
	v_and_b32_e32 v69, 0xffff0000, v69
	v_lshlrev_b32_e32 v78, 16, v70
	v_and_b32_e32 v79, 0xffff0000, v70
	v_lshlrev_b32_e32 v70, 16, v71
	v_and_b32_e32 v71, 0xffff0000, v71
	v_pk_fma_f32 v[0:1], v[140:141], v[124:125], v[0:1] op_sel_hi:[1,0,1]
	v_pk_fma_f32 v[2:3], v[138:139], v[124:125], v[2:3] op_sel_hi:[1,0,1]
	v_pk_fma_f32 v[4:5], v[136:137], v[124:125], v[4:5] op_sel_hi:[1,0,1]
	v_pk_fma_f32 v[6:7], v[134:135], v[124:125], v[6:7] op_sel_hi:[1,0,1]
	v_pk_fma_f32 v[8:9], v[8:9], v[124:125], v[76:77] op_sel_hi:[1,0,1]
	v_pk_fma_f32 v[10:11], v[10:11], v[124:125], v[68:69] op_sel_hi:[1,0,1]
	v_pk_fma_f32 v[12:13], v[12:13], v[124:125], v[78:79] op_sel_hi:[1,0,1]
	v_pk_fma_f32 v[14:15], v[14:15], v[124:125], v[70:71] op_sel_hi:[1,0,1]
	ds_read_b128 v[76:79], v115 offset:10240
	ds_read_b128 v[138:141], v115 offset:11264
	ds_read_b128 v[252:255], v115 offset:12288
	ds_read_b128 v[202:205], v115 offset:13312
	s_waitcnt lgkmcnt(5)
	v_mfma_f32_32x32x16_bf16 v[0:15], v[16:19], v[24:27], v[0:15]
	v_add_u32_e32 v125, s21, v128
	v_add_u32_e32 v127, s23, v128
	s_waitcnt lgkmcnt(4)
	v_mfma_f32_32x32x16_bf16 v[16:31], v[20:23], v[28:31], 0
	v_add_u32_e32 v146, 5, v201
	v_min_u32_e32 v146, 0x7f, v146
	v_lshl_add_u32 v146, v146, 17, v128
	v_add_u32_e32 v147, 0x1000, v146
	s_waitcnt vmcnt(43)
	s_waitcnt lgkmcnt(3)
	v_mfma_f32_32x32x16_bf16 v[0:15], v[172:175], v[76:79], v[0:15]
	global_load_dwordx4 v[172:175], v146, s[100:101] offset:2048
	s_waitcnt vmcnt(43)
	s_waitcnt lgkmcnt(2)
	v_mfma_f32_32x32x16_bf16 v[16:31], v[176:179], v[138:141], v[16:31]
	global_load_dwordx4 v[176:179], v146, s[100:101] offset:3072
	ds_read_b128 v[76:79], v115 offset:14336
	ds_read_b128 v[138:141], v115 offset:15360
	s_waitcnt vmcnt(43)
	s_waitcnt lgkmcnt(3)
	v_mfma_f32_32x32x16_bf16 v[0:15], v[180:183], v[252:255], v[0:15]
	global_load_dwordx4 v[180:183], v147, s[100:101]
	v_lshl_add_u64 v[68:69], s[92:93], 0, v[108:109]
	v_add_co_u32_e32 v142, vcc, s28, v68
	v_lshl_add_u64 v[108:109], v[108:109], 0, s[8:9]
	s_nop 0
	v_addc_co_u32_e32 v143, vcc, 0, v69, vcc
	s_waitcnt vmcnt(43)
	s_waitcnt lgkmcnt(2)
	v_mfma_f32_32x32x16_bf16 v[16:31], v[184:187], v[202:205], v[16:31]
	global_load_dwordx4 v[184:187], v147, s[100:101] offset:1024
	s_waitcnt vmcnt(43)
	s_waitcnt lgkmcnt(1)
	v_mfma_f32_32x32x16_bf16 v[0:15], v[188:191], v[76:79], v[0:15]
	global_load_dwordx4 v[188:191], v147, s[100:101] offset:2048
	v_mov_b32_e32 v68, s30
	s_lshl_b32 s30, s6, 2
	s_lshl_b32 s6, s6, 15
	s_waitcnt vmcnt(43)
	s_waitcnt lgkmcnt(0)
	v_mfma_f32_32x32x16_bf16 v[16:31], v[192:195], v[138:141], v[16:31]
	global_load_dwordx4 v[192:195], v147, s[100:101] offset:3072
	s_nop 11
	v_pk_add_f32 v[134:135], v[6:7], v[22:23]
	v_pk_add_f32 v[136:137], v[4:5], v[20:21]
	v_pk_add_f32 v[138:139], v[2:3], v[18:19]
	v_pk_add_f32 v[140:141], v[0:1], v[16:17]
	v_pk_add_f32 v[14:15], v[14:15], v[30:31]
	v_pk_add_f32 v[12:13], v[12:13], v[28:29]
	v_pk_add_f32 v[10:11], v[10:11], v[26:27]
	v_pk_add_f32 v[8:9], v[8:9], v[24:25]
	v_cvt_pk_bf16_f32 v0, v140, v141
	v_cvt_pk_bf16_f32 v1, v138, v139
	v_cvt_pk_bf16_f32 v2, v136, v137
	v_cvt_pk_bf16_f32 v3, v134, v135
	v_cvt_pk_bf16_f32 v4, v8, v9
	v_cvt_pk_bf16_f32 v5, v10, v11
	v_cvt_pk_bf16_f32 v6, v12, v13
	v_cvt_pk_bf16_f32 v7, v14, v15
	ds_write_b128 v119, v[0:3]
	ds_write_b128 v119, v[4:7] offset:1024
	global_store_dwordx4 v[142:143], v[0:3], off
	global_store_dwordx4 v[142:143], v[4:7], off offset:1024
	s_waitcnt lgkmcnt(0)
	s_barrier
	global_load_dword v124, v68, s[4:5]
	global_load_dwordx4 v[76:79], v[144:145], off
	s_nop 0
	global_load_dwordx4 v[68:71], v[144:145], off offset:1024
	ds_read_b128 v[16:19], v125
	ds_read_b128 v[20:23], v125 offset:1024
	ds_read_b128 v[24:27], v115
	ds_read_b128 v[28:31], v115 offset:1024
	v_lshlrev_b32_e32 v0, 16, v84
	v_and_b32_e32 v1, 0xffff0000, v84
	v_lshlrev_b32_e32 v2, 16, v85
	v_and_b32_e32 v3, 0xffff0000, v85
	v_lshlrev_b32_e32 v4, 16, v86
	v_and_b32_e32 v5, 0xffff0000, v86
	v_lshlrev_b32_e32 v6, 16, v87
	v_and_b32_e32 v7, 0xffff0000, v87
	v_lshlrev_b32_e32 v84, 16, v80
	v_and_b32_e32 v85, 0xffff0000, v80
	v_lshlrev_b32_e32 v80, 16, v81
	v_and_b32_e32 v81, 0xffff0000, v81
	v_lshlrev_b32_e32 v86, 16, v82
	v_and_b32_e32 v87, 0xffff0000, v82
	v_lshlrev_b32_e32 v82, 16, v83
	v_and_b32_e32 v83, 0xffff0000, v83
	v_pk_fma_f32 v[0:1], v[140:141], v[122:123], v[0:1] op_sel_hi:[1,0,1]
	v_pk_fma_f32 v[2:3], v[138:139], v[122:123], v[2:3] op_sel_hi:[1,0,1]
	v_pk_fma_f32 v[4:5], v[136:137], v[122:123], v[4:5] op_sel_hi:[1,0,1]
	v_pk_fma_f32 v[6:7], v[134:135], v[122:123], v[6:7] op_sel_hi:[1,0,1]
	v_pk_fma_f32 v[8:9], v[8:9], v[122:123], v[84:85] op_sel_hi:[1,0,1]
	v_pk_fma_f32 v[10:11], v[10:11], v[122:123], v[80:81] op_sel_hi:[1,0,1]
	v_pk_fma_f32 v[12:13], v[12:13], v[122:123], v[86:87] op_sel_hi:[1,0,1]
	v_pk_fma_f32 v[14:15], v[14:15], v[122:123], v[82:83] op_sel_hi:[1,0,1]
	ds_read_b128 v[84:87], v115 offset:2048
	ds_read_b128 v[138:141], v115 offset:3072
	ds_read_b128 v[252:255], v115 offset:4096
	ds_read_b128 v[202:205], v115 offset:5120
	s_waitcnt lgkmcnt(5)
; __device__ __forceinline__ void scan_step(const ScanB& p, f32x16& acc, unsigned char* ws, LAS unsigned char* lds, int bh, int n, int cur, int td, int te, int lane) {
;     const int item = scan_item(bh, n);
;     v4u b0 = p.bn[0], b1 = p.bn[1]; float egl = p.egl;
;     asm volatile("" : "+v"(egl)); asm volatile("" : "+v"(b0)); asm volatile("" : "+v"(b1));
;     f32x16 bv16; ans_unpack(b0, b1, bv16);
; #pragma unroll
;     for (int r = 0; r < 16; ++r) acc[r] = acc[r] * egl + bv16[r];
;     const LAS unsigned char* sb = lds + cur * 8192 + lane * 16;
;     const LAS unsigned char* sa = lds + SC_RING + (n & 3) * SC_SLOT + td * 8192 + lane * 16;
;     f32x16 acc2 = zero16();
; #pragma unroll
;     for (int q = 0; q < 8; q += 2) {
;         const bf16x8 a0 = *(const LAS bf16x8*)(sa + 1024 * q), bv0 = *(const LAS bf16x8*)(sb + 1024 * q);
;         const bf16x8 a1 = *(const LAS bf16x8*)(sa + 1024 * (q + 1)), bv1 = *(const LAS bf16x8*)(sb + 1024 * (q + 1));
;         acc = __builtin_amdgcn_mfma_f32_32x32x16_bf16(a0, bv0, acc, 0, 0, 0); acc2 = __builtin_amdgcn_mfma_f32_32x32x16_bf16(a1, bv1, acc2, 0, 0, 0); }
; #pragma unroll
;     for (int r = 0; r < 16; ++r) acc[r] += acc2[r];
;     v4u w0, w1; ans_pack(acc, w0, w1);
;     LAS unsigned char* sn = lds + (cur ^ 1) * 8192 + td * 2048 + lane * 16;
;     *(LAS v4u*)sn = w0; *(LAS v4u*)(sn + 1024) = w1;
;     bf16* So = (bf16*)(ws + WS_BS) + (size_t)item * 16384 + (te * 4 + td) * 1024 + lane * 8;
;     *(v4u*)So = w0; *(v4u*)(So + 512) = w1;
; __device__ __forceinline__ void dn_scan(const Args& a, LAS unsigned char* lds, int wg, int tid, int wave, int lane) {
;     ...
;             scanb_load(p7, ws, bh, n + 7, td, te, lane);  scan_step(p0, acc, ws, lds, bh, n, 0, td, te, lane); WG_BAR();
;             scanb_load(p0, ws, bh, n + 8, td, te, lane);  scan_step(p1, acc, ws, lds, bh, n + 1, 1, td, te, lane); WG_BAR();
;             scanb_load(p1, ws, bh, n + 9, td, te, lane);  scan_step(p2, acc, ws, lds, bh, n + 2, 0, td, te, lane); WG_BAR();
;             scanb_load(p2, ws, bh, n + 10, td, te, lane); scan_step(p3, acc, ws, lds, bh, n + 3, 1, td, te, lane); WG_BAR();
;             scanb_load(p3, ws, bh, n + 11, td, te, lane); scan_step(p4, acc, ws, lds, bh, n + 4, 0, td, te, lane); WG_BAR();
;             scanb_load(p4, ws, bh, n + 12, td, te, lane); scan_step(p5, acc, ws, lds, bh, n + 5, 1, td, te, lane); WG_BAR();
	v_mfma_f32_32x32x16_bf16 v[0:15], v[16:19], v[24:27], v[0:15]
	v_lshl_add_u64 v[144:145], v[96:97], 0, s[6:7]
	s_min_u32 s6, s29, 0x74
	s_add_i32 s6, s24, s6
	s_lshl_b32 s6, s6, 2
	s_or_b32 s6, s6, s13
	s_waitcnt lgkmcnt(4)
	v_mfma_f32_32x32x16_bf16 v[16:31], v[20:23], v[28:31], 0
	v_add_u32_e32 v146, 6, v201
	v_min_u32_e32 v146, 0x7f, v146
	v_lshl_add_u32 v146, v146, 17, v128
	v_add_u32_e32 v147, 0x1000, v146
	s_waitcnt vmcnt(43)
	s_waitcnt lgkmcnt(3)
	v_mfma_f32_32x32x16_bf16 v[0:15], v[196:199], v[84:87], v[0:15]
	global_load_dwordx4 v[196:199], v146, s[100:101] offset:2048
	s_waitcnt vmcnt(43)
	s_waitcnt lgkmcnt(2)
	v_mfma_f32_32x32x16_bf16 v[16:31], v[208:211], v[138:141], v[16:31]
	global_load_dwordx4 v[208:211], v146, s[100:101] offset:3072
	ds_read_b128 v[84:87], v115 offset:6144
	ds_read_b128 v[138:141], v115 offset:7168
	s_waitcnt vmcnt(43)
	s_waitcnt lgkmcnt(3)
	v_mfma_f32_32x32x16_bf16 v[0:15], v[212:215], v[252:255], v[0:15]
	global_load_dwordx4 v[212:215], v147, s[100:101]
	v_lshl_add_u64 v[80:81], s[92:93], 0, v[106:107]
	v_add_co_u32_e32 v142, vcc, s28, v80
	v_lshl_add_u64 v[106:107], v[106:107], 0, s[8:9]
	s_nop 0
	v_addc_co_u32_e32 v143, vcc, 0, v81, vcc
	s_waitcnt vmcnt(43)
	s_waitcnt lgkmcnt(2)
	v_mfma_f32_32x32x16_bf16 v[16:31], v[216:219], v[202:205], v[16:31]
	global_load_dwordx4 v[216:219], v147, s[100:101] offset:1024
	s_waitcnt vmcnt(43)
	s_waitcnt lgkmcnt(1)
	v_mfma_f32_32x32x16_bf16 v[0:15], v[220:223], v[84:87], v[0:15]
	global_load_dwordx4 v[220:223], v147, s[100:101] offset:2048
	v_mov_b32_e32 v80, s30
	s_lshl_b32 s30, s6, 2
	s_lshl_b32 s6, s6, 15
	s_waitcnt vmcnt(43)
	s_waitcnt lgkmcnt(0)
	v_mfma_f32_32x32x16_bf16 v[16:31], v[224:227], v[138:141], v[16:31]
	global_load_dwordx4 v[224:227], v147, s[100:101] offset:3072
	s_nop 11
	v_pk_add_f32 v[134:135], v[6:7], v[22:23]
	v_pk_add_f32 v[136:137], v[4:5], v[20:21]
	v_pk_add_f32 v[138:139], v[2:3], v[18:19]
	v_pk_add_f32 v[140:141], v[0:1], v[16:17]
	v_pk_add_f32 v[14:15], v[14:15], v[30:31]
	v_pk_add_f32 v[12:13], v[12:13], v[28:29]
	v_pk_add_f32 v[10:11], v[10:11], v[26:27]
	v_pk_add_f32 v[8:9], v[8:9], v[24:25]
	v_cvt_pk_bf16_f32 v0, v140, v141
	v_cvt_pk_bf16_f32 v1, v138, v139
	v_cvt_pk_bf16_f32 v2, v136, v137
	v_cvt_pk_bf16_f32 v3, v134, v135
	v_cvt_pk_bf16_f32 v4, v8, v9
	v_cvt_pk_bf16_f32 v5, v10, v11
	v_cvt_pk_bf16_f32 v6, v12, v13
	v_cvt_pk_bf16_f32 v7, v14, v15
	ds_write_b128 v117, v[0:3] offset:8192
	ds_write_b128 v117, v[4:7] offset:9216
	global_store_dwordx4 v[142:143], v[0:3], off
	global_store_dwordx4 v[142:143], v[4:7], off offset:1024
	s_waitcnt lgkmcnt(0)
	s_barrier
	global_load_dword v122, v80, s[4:5]
	global_load_dwordx4 v[84:87], v[144:145], off
	s_nop 0
	global_load_dwordx4 v[80:83], v[144:145], off offset:1024
	ds_read_b128 v[16:19], v127
	ds_read_b128 v[20:23], v127 offset:1024
	ds_read_b128 v[24:27], v115 offset:8192
	ds_read_b128 v[28:31], v115 offset:9216
	v_lshlrev_b32_e32 v0, 16, v36
	v_and_b32_e32 v1, 0xffff0000, v36
	v_lshlrev_b32_e32 v2, 16, v37
	v_and_b32_e32 v3, 0xffff0000, v37
	v_lshlrev_b32_e32 v4, 16, v38
	v_and_b32_e32 v5, 0xffff0000, v38
	v_lshlrev_b32_e32 v6, 16, v39
	v_and_b32_e32 v7, 0xffff0000, v39
	v_lshlrev_b32_e32 v36, 16, v32
	v_and_b32_e32 v37, 0xffff0000, v32
	v_lshlrev_b32_e32 v32, 16, v33
	v_and_b32_e32 v33, 0xffff0000, v33
	v_lshlrev_b32_e32 v38, 16, v34
	v_and_b32_e32 v39, 0xffff0000, v34
	v_lshlrev_b32_e32 v34, 16, v35
	v_and_b32_e32 v35, 0xffff0000, v35
	v_pk_fma_f32 v[0:1], v[140:141], v[114:115], v[0:1] op_sel_hi:[1,0,1]
	v_pk_fma_f32 v[2:3], v[138:139], v[114:115], v[2:3] op_sel_hi:[1,0,1]
	v_pk_fma_f32 v[4:5], v[136:137], v[114:115], v[4:5] op_sel_hi:[1,0,1]
	v_pk_fma_f32 v[6:7], v[134:135], v[114:115], v[6:7] op_sel_hi:[1,0,1]
	v_pk_fma_f32 v[8:9], v[8:9], v[114:115], v[36:37] op_sel_hi:[1,0,1]
	v_pk_fma_f32 v[10:11], v[10:11], v[114:115], v[32:33] op_sel_hi:[1,0,1]
	v_pk_fma_f32 v[12:13], v[12:13], v[114:115], v[38:39] op_sel_hi:[1,0,1]
	v_pk_fma_f32 v[14:15], v[14:15], v[114:115], v[34:35] op_sel_hi:[1,0,1]
	ds_read_b128 v[36:39], v115 offset:10240
	ds_read_b128 v[138:141], v115 offset:11264
	ds_read_b128 v[252:255], v115 offset:12288
	ds_read_b128 v[202:205], v115 offset:13312
	s_waitcnt lgkmcnt(5)
	v_mfma_f32_32x32x16_bf16 v[0:15], v[16:19], v[24:27], v[0:15]
	v_lshl_add_u64 v[144:145], v[96:97], 0, s[6:7]
	s_min_u32 s6, s29, 0x73
	s_add_i32 s6, s25, s6
	s_lshl_b32 s6, s6, 2
	s_or_b32 s6, s6, s13
	s_waitcnt lgkmcnt(4)
	v_mfma_f32_32x32x16_bf16 v[16:31], v[20:23], v[28:31], 0
	v_add_u32_e32 v146, 7, v201
	v_min_u32_e32 v146, 0x7f, v146
	v_lshl_add_u32 v146, v146, 17, v128
	v_add_u32_e32 v147, 0x1000, v146
	s_waitcnt vmcnt(43)
	s_waitcnt lgkmcnt(3)
	v_mfma_f32_32x32x16_bf16 v[0:15], v[228:231], v[36:39], v[0:15]
	global_load_dwordx4 v[228:231], v146, s[100:101] offset:2048
	s_waitcnt vmcnt(43)
	s_waitcnt lgkmcnt(2)
	v_mfma_f32_32x32x16_bf16 v[16:31], v[232:235], v[138:141], v[16:31]
	global_load_dwordx4 v[232:235], v146, s[100:101] offset:3072
	ds_read_b128 v[36:39], v115 offset:14336
	ds_read_b128 v[138:141], v115 offset:15360
	s_waitcnt vmcnt(43)
	s_waitcnt lgkmcnt(3)
	v_mfma_f32_32x32x16_bf16 v[0:15], v[236:239], v[252:255], v[0:15]
	global_load_dwordx4 v[236:239], v147, s[100:101]
	v_lshl_add_u64 v[32:33], s[92:93], 0, v[104:105]
	v_add_co_u32_e32 v142, vcc, s28, v32
	v_lshl_add_u64 v[104:105], v[104:105], 0, s[8:9]
	s_nop 0
	v_addc_co_u32_e32 v143, vcc, 0, v33, vcc
	s_waitcnt vmcnt(43)
	s_waitcnt lgkmcnt(2)
	v_mfma_f32_32x32x16_bf16 v[16:31], v[240:243], v[202:205], v[16:31]
	global_load_dwordx4 v[240:243], v147, s[100:101] offset:1024
	s_waitcnt vmcnt(43)
	s_waitcnt lgkmcnt(1)
	v_mfma_f32_32x32x16_bf16 v[0:15], v[244:247], v[36:39], v[0:15]
	global_load_dwordx4 v[244:247], v147, s[100:101] offset:2048
	v_mov_b32_e32 v32, s30
	s_lshl_b32 s30, s6, 2
	s_lshl_b32 s6, s6, 15
	s_waitcnt vmcnt(43)
	s_waitcnt lgkmcnt(0)
	v_mfma_f32_32x32x16_bf16 v[16:31], v[248:251], v[138:141], v[16:31]
	global_load_dwordx4 v[248:251], v147, s[100:101] offset:3072
	s_nop 11
	v_pk_add_f32 v[134:135], v[6:7], v[22:23]
	v_pk_add_f32 v[136:137], v[4:5], v[20:21]
	v_pk_add_f32 v[138:139], v[2:3], v[18:19]
	v_pk_add_f32 v[140:141], v[0:1], v[16:17]
	v_pk_add_f32 v[14:15], v[14:15], v[30:31]
	v_pk_add_f32 v[12:13], v[12:13], v[28:29]
	v_pk_add_f32 v[10:11], v[10:11], v[26:27]
	v_pk_add_f32 v[8:9], v[8:9], v[24:25]
	v_cvt_pk_bf16_f32 v0, v140, v141
	v_cvt_pk_bf16_f32 v1, v138, v139
	v_cvt_pk_bf16_f32 v2, v136, v137
	v_cvt_pk_bf16_f32 v3, v134, v135
	v_cvt_pk_bf16_f32 v4, v8, v9
	v_cvt_pk_bf16_f32 v5, v10, v11
	v_cvt_pk_bf16_f32 v6, v12, v13
	v_cvt_pk_bf16_f32 v7, v14, v15
	ds_write_b128 v119, v[0:3]
	ds_write_b128 v119, v[4:7] offset:1024
	global_store_dwordx4 v[142:143], v[0:3], off
	global_store_dwordx4 v[142:143], v[4:7], off offset:1024
	s_waitcnt lgkmcnt(0)
	s_barrier
; __device__ __forceinline__ void scan_step(const ScanB& p, f32x16& acc, unsigned char* ws, LAS unsigned char* lds, int bh, int n, int cur, int td, int te, int lane) {
;     const int item = scan_item(bh, n);
;     v4u b0 = p.bn[0], b1 = p.bn[1]; float egl = p.egl;
;     asm volatile("" : "+v"(egl)); asm volatile("" : "+v"(b0)); asm volatile("" : "+v"(b1));
;     f32x16 bv16; ans_unpack(b0, b1, bv16);
; #pragma unroll
;     for (int r = 0; r < 16; ++r) acc[r] = acc[r] * egl + bv16[r];
;     const LAS unsigned char* sb = lds + cur * 8192 + lane * 16;
;     const LAS unsigned char* sa = lds + SC_RING + (n & 3) * SC_SLOT + td * 8192 + lane * 16;
;     f32x16 acc2 = zero16();
; #pragma unroll
;     for (int q = 0; q < 8; q += 2) {
;         const bf16x8 a0 = *(const LAS bf16x8*)(sa + 1024 * q), bv0 = *(const LAS bf16x8*)(sb + 1024 * q);
;         const bf16x8 a1 = *(const LAS bf16x8*)(sa + 1024 * (q + 1)), bv1 = *(const LAS bf16x8*)(sb + 1024 * (q + 1));
;         acc = __builtin_amdgcn_mfma_f32_32x32x16_bf16(a0, bv0, acc, 0, 0, 0); acc2 = __builtin_amdgcn_mfma_f32_32x32x16_bf16(a1, bv1, acc2, 0, 0, 0); }
; #pragma unroll
;     for (int r = 0; r < 16; ++r) acc[r] += acc2[r];
;     v4u w0, w1; ans_pack(acc, w0, w1);
;     LAS unsigned char* sn = lds + (cur ^ 1) * 8192 + td * 2048 + lane * 16;
;     *(LAS v4u*)sn = w0; *(LAS v4u*)(sn + 1024) = w1;
;     bf16* So = (bf16*)(ws + WS_BS) + (size_t)item * 16384 + (te * 4 + td) * 1024 + lane * 8;
;     *(v4u*)So = w0; *(v4u*)(So + 512) = w1;
; __device__ __forceinline__ void dn_scan(const Args& a, LAS unsigned char* lds, int wg, int tid, int wave, int lane) {
;     ...
;             scanb_load(p7, ws, bh, n + 7, td, te, lane);  scan_step(p0, acc, ws, lds, bh, n, 0, td, te, lane); WG_BAR();
;             scanb_load(p0, ws, bh, n + 8, td, te, lane);  scan_step(p1, acc, ws, lds, bh, n + 1, 1, td, te, lane); WG_BAR();
;             scanb_load(p1, ws, bh, n + 9, td, te, lane);  scan_step(p2, acc, ws, lds, bh, n + 2, 0, td, te, lane); WG_BAR();
;             scanb_load(p2, ws, bh, n + 10, td, te, lane); scan_step(p3, acc, ws, lds, bh, n + 3, 1, td, te, lane); WG_BAR();
;             scanb_load(p3, ws, bh, n + 11, td, te, lane); scan_step(p4, acc, ws, lds, bh, n + 4, 0, td, te, lane); WG_BAR();
;             scanb_load(p4, ws, bh, n + 12, td, te, lane); scan_step(p5, acc, ws, lds, bh, n + 5, 1, td, te, lane); WG_BAR();
	global_load_dword v114, v32, s[4:5]
	global_load_dwordx4 v[36:39], v[144:145], off
	s_nop 0
	global_load_dwordx4 v[32:35], v[144:145], off offset:1024
	ds_read_b128 v[16:19], v123 offset:16384
	ds_read_b128 v[20:23], v123 offset:17408
	ds_read_b128 v[24:27], v115
	ds_read_b128 v[28:31], v115 offset:1024
	v_lshlrev_b32_e32 v0, 16, v44
	v_and_b32_e32 v1, 0xffff0000, v44
	v_lshlrev_b32_e32 v2, 16, v45
	v_and_b32_e32 v3, 0xffff0000, v45
	v_lshlrev_b32_e32 v4, 16, v46
	v_and_b32_e32 v5, 0xffff0000, v46
	v_lshlrev_b32_e32 v6, 16, v47
	v_and_b32_e32 v7, 0xffff0000, v47
	v_lshlrev_b32_e32 v44, 16, v40
	v_and_b32_e32 v45, 0xffff0000, v40
	v_lshlrev_b32_e32 v40, 16, v41
	v_and_b32_e32 v41, 0xffff0000, v41
	v_lshlrev_b32_e32 v46, 16, v42
	v_and_b32_e32 v47, 0xffff0000, v42
	v_lshlrev_b32_e32 v42, 16, v43
	v_and_b32_e32 v43, 0xffff0000, v43
	v_pk_fma_f32 v[0:1], v[140:141], v[116:117], v[0:1] op_sel_hi:[1,0,1]
	v_pk_fma_f32 v[2:3], v[138:139], v[116:117], v[2:3] op_sel_hi:[1,0,1]
	v_pk_fma_f32 v[4:5], v[136:137], v[116:117], v[4:5] op_sel_hi:[1,0,1]
	v_pk_fma_f32 v[6:7], v[134:135], v[116:117], v[6:7] op_sel_hi:[1,0,1]
	v_pk_fma_f32 v[8:9], v[8:9], v[116:117], v[44:45] op_sel_hi:[1,0,1]
	v_pk_fma_f32 v[10:11], v[10:11], v[116:117], v[40:41] op_sel_hi:[1,0,1]
	v_pk_fma_f32 v[12:13], v[12:13], v[116:117], v[46:47] op_sel_hi:[1,0,1]
	v_pk_fma_f32 v[14:15], v[14:15], v[116:117], v[42:43] op_sel_hi:[1,0,1]
	ds_read_b128 v[44:47], v115 offset:2048
	ds_read_b128 v[138:141], v115 offset:3072
	ds_read_b128 v[252:255], v115 offset:4096
	ds_read_b128 v[202:205], v115 offset:5120
	s_waitcnt lgkmcnt(5)
	v_mfma_f32_32x32x16_bf16 v[0:15], v[16:19], v[24:27], v[0:15]
	v_lshl_add_u64 v[144:145], v[96:97], 0, s[6:7]
	s_min_u32 s6, s29, 0x72
	s_add_i32 s6, s26, s6
	s_lshl_b32 s6, s6, 2
	s_or_b32 s6, s6, s13
	s_waitcnt lgkmcnt(4)
	v_mfma_f32_32x32x16_bf16 v[16:31], v[20:23], v[28:31], 0
	v_add_u32_e32 v146, 8, v201
	v_min_u32_e32 v146, 0x7f, v146
	v_lshl_add_u32 v146, v146, 17, v128
	v_add_u32_e32 v147, 0x1000, v146
	s_waitcnt vmcnt(43)
	s_waitcnt lgkmcnt(3)
	v_mfma_f32_32x32x16_bf16 v[0:15], v[148:151], v[44:47], v[0:15]
	global_load_dwordx4 v[148:151], v146, s[100:101] offset:2048
	s_waitcnt vmcnt(43)
	s_waitcnt lgkmcnt(2)
	v_mfma_f32_32x32x16_bf16 v[16:31], v[152:155], v[138:141], v[16:31]
	global_load_dwordx4 v[152:155], v146, s[100:101] offset:3072
	ds_read_b128 v[44:47], v115 offset:6144
	ds_read_b128 v[138:141], v115 offset:7168
	s_waitcnt vmcnt(43)
	s_waitcnt lgkmcnt(3)
	v_mfma_f32_32x32x16_bf16 v[0:15], v[156:159], v[252:255], v[0:15]
	global_load_dwordx4 v[156:159], v147, s[100:101]
	v_lshl_add_u64 v[40:41], s[92:93], 0, v[102:103]
	v_add_co_u32_e32 v142, vcc, s28, v40
	v_lshl_add_u64 v[102:103], v[102:103], 0, s[8:9]
	s_nop 0
	v_addc_co_u32_e32 v143, vcc, 0, v41, vcc
	s_waitcnt vmcnt(43)
	s_waitcnt lgkmcnt(2)
	v_mfma_f32_32x32x16_bf16 v[16:31], v[160:163], v[202:205], v[16:31]
	global_load_dwordx4 v[160:163], v147, s[100:101] offset:1024
	s_waitcnt vmcnt(43)
	s_waitcnt lgkmcnt(1)
	v_mfma_f32_32x32x16_bf16 v[0:15], v[164:167], v[44:47], v[0:15]
	global_load_dwordx4 v[164:167], v147, s[100:101] offset:2048
	v_mov_b32_e32 v40, s30
	s_lshl_b32 s30, s6, 2
	s_lshl_b32 s6, s6, 15
	s_waitcnt vmcnt(43)
	s_waitcnt lgkmcnt(0)
	v_mfma_f32_32x32x16_bf16 v[16:31], v[168:171], v[138:141], v[16:31]
	global_load_dwordx4 v[168:171], v147, s[100:101] offset:3072
	s_nop 11
	v_pk_add_f32 v[134:135], v[6:7], v[22:23]
	v_pk_add_f32 v[136:137], v[4:5], v[20:21]
	v_pk_add_f32 v[138:139], v[2:3], v[18:19]
	v_pk_add_f32 v[140:141], v[0:1], v[16:17]
	v_pk_add_f32 v[14:15], v[14:15], v[30:31]
	v_pk_add_f32 v[12:13], v[12:13], v[28:29]
	v_pk_add_f32 v[10:11], v[10:11], v[26:27]
	v_pk_add_f32 v[8:9], v[8:9], v[24:25]
	v_cvt_pk_bf16_f32 v0, v140, v141
	v_cvt_pk_bf16_f32 v1, v138, v139
	v_cvt_pk_bf16_f32 v2, v136, v137
	v_cvt_pk_bf16_f32 v3, v134, v135
	v_cvt_pk_bf16_f32 v4, v8, v9
	v_cvt_pk_bf16_f32 v5, v10, v11
	v_cvt_pk_bf16_f32 v6, v12, v13
	v_cvt_pk_bf16_f32 v7, v14, v15
	ds_write_b128 v117, v[0:3] offset:8192
	ds_write_b128 v117, v[4:7] offset:9216
	global_store_dwordx4 v[142:143], v[0:3], off
	global_store_dwordx4 v[142:143], v[4:7], off offset:1024
	s_waitcnt lgkmcnt(0)
	s_barrier
	global_load_dword v116, v40, s[4:5]
	global_load_dwordx4 v[44:47], v[144:145], off
	s_nop 0
	global_load_dwordx4 v[40:43], v[144:145], off offset:1024
	ds_read_b128 v[16:19], v121 offset:49152
	ds_read_b128 v[20:23], v121 offset:50176
	ds_read_b128 v[24:27], v115 offset:8192
	ds_read_b128 v[28:31], v115 offset:9216
	v_lshlrev_b32_e32 v0, 16, v52
	v_and_b32_e32 v1, 0xffff0000, v52
	v_lshlrev_b32_e32 v2, 16, v53
	v_and_b32_e32 v3, 0xffff0000, v53
	v_lshlrev_b32_e32 v4, 16, v54
	v_and_b32_e32 v5, 0xffff0000, v54
	v_lshlrev_b32_e32 v6, 16, v55
	v_and_b32_e32 v7, 0xffff0000, v55
	v_lshlrev_b32_e32 v52, 16, v48
	v_and_b32_e32 v53, 0xffff0000, v48
	v_lshlrev_b32_e32 v48, 16, v49
	v_and_b32_e32 v49, 0xffff0000, v49
	v_lshlrev_b32_e32 v54, 16, v50
	v_and_b32_e32 v55, 0xffff0000, v50
	v_lshlrev_b32_e32 v50, 16, v51
	v_and_b32_e32 v51, 0xffff0000, v51
	v_pk_fma_f32 v[0:1], v[140:141], v[118:119], v[0:1] op_sel_hi:[1,0,1]
	v_pk_fma_f32 v[2:3], v[138:139], v[118:119], v[2:3] op_sel_hi:[1,0,1]
	v_pk_fma_f32 v[4:5], v[136:137], v[118:119], v[4:5] op_sel_hi:[1,0,1]
	v_pk_fma_f32 v[6:7], v[134:135], v[118:119], v[6:7] op_sel_hi:[1,0,1]
	v_pk_fma_f32 v[8:9], v[8:9], v[118:119], v[52:53] op_sel_hi:[1,0,1]
	v_pk_fma_f32 v[10:11], v[10:11], v[118:119], v[48:49] op_sel_hi:[1,0,1]
	v_pk_fma_f32 v[12:13], v[12:13], v[118:119], v[54:55] op_sel_hi:[1,0,1]
	v_pk_fma_f32 v[14:15], v[14:15], v[118:119], v[50:51] op_sel_hi:[1,0,1]
	ds_read_b128 v[52:55], v115 offset:10240
	ds_read_b128 v[138:141], v115 offset:11264
	ds_read_b128 v[252:255], v115 offset:12288
	ds_read_b128 v[202:205], v115 offset:13312
	s_waitcnt lgkmcnt(5)
; __device__ __forceinline__ void scan_step(const ScanB& p, f32x16& acc, unsigned char* ws, LAS unsigned char* lds, int bh, int n, int cur, int td, int te, int lane) {
;     const int item = scan_item(bh, n);
;     v4u b0 = p.bn[0], b1 = p.bn[1]; float egl = p.egl;
;     asm volatile("" : "+v"(egl)); asm volatile("" : "+v"(b0)); asm volatile("" : "+v"(b1));
;     f32x16 bv16; ans_unpack(b0, b1, bv16);
; #pragma unroll
;     for (int r = 0; r < 16; ++r) acc[r] = acc[r] * egl + bv16[r];
;     const LAS unsigned char* sb = lds + cur * 8192 + lane * 16;
;     const LAS unsigned char* sa = lds + SC_RING + (n & 3) * SC_SLOT + td * 8192 + lane * 16;
;     f32x16 acc2 = zero16();
; #pragma unroll
;     for (int q = 0; q < 8; q += 2) {
;         const bf16x8 a0 = *(const LAS bf16x8*)(sa + 1024 * q), bv0 = *(const LAS bf16x8*)(sb + 1024 * q);
;         const bf16x8 a1 = *(const LAS bf16x8*)(sa + 1024 * (q + 1)), bv1 = *(const LAS bf16x8*)(sb + 1024 * (q + 1));
;         acc = __builtin_amdgcn_mfma_f32_32x32x16_bf16(a0, bv0, acc, 0, 0, 0); acc2 = __builtin_amdgcn_mfma_f32_32x32x16_bf16(a1, bv1, acc2, 0, 0, 0); }
; #pragma unroll
;     for (int r = 0; r < 16; ++r) acc[r] += acc2[r];
;     v4u w0, w1; ans_pack(acc, w0, w1);
;     LAS unsigned char* sn = lds + (cur ^ 1) * 8192 + td * 2048 + lane * 16;
;     *(LAS v4u*)sn = w0; *(LAS v4u*)(sn + 1024) = w1;
;     bf16* So = (bf16*)(ws + WS_BS) + (size_t)item * 16384 + (te * 4 + td) * 1024 + lane * 8;
;     *(v4u*)So = w0; *(v4u*)(So + 512) = w1;
; __device__ __forceinline__ void dn_scan(const Args& a, LAS unsigned char* lds, int wg, int tid, int wave, int lane) {
;     ...
;             scanb_load(p7, ws, bh, n + 7, td, te, lane);  scan_step(p0, acc, ws, lds, bh, n, 0, td, te, lane); WG_BAR();
;             scanb_load(p0, ws, bh, n + 8, td, te, lane);  scan_step(p1, acc, ws, lds, bh, n + 1, 1, td, te, lane); WG_BAR();
;             scanb_load(p1, ws, bh, n + 9, td, te, lane);  scan_step(p2, acc, ws, lds, bh, n + 2, 0, td, te, lane); WG_BAR();
;             scanb_load(p2, ws, bh, n + 10, td, te, lane); scan_step(p3, acc, ws, lds, bh, n + 3, 1, td, te, lane); WG_BAR();
;             scanb_load(p3, ws, bh, n + 11, td, te, lane); scan_step(p4, acc, ws, lds, bh, n + 4, 0, td, te, lane); WG_BAR();
;             scanb_load(p4, ws, bh, n + 12, td, te, lane); scan_step(p5, acc, ws, lds, bh, n + 5, 1, td, te, lane); WG_BAR();
	v_mfma_f32_32x32x16_bf16 v[0:15], v[16:19], v[24:27], v[0:15]
	v_lshl_add_u64 v[144:145], v[96:97], 0, s[6:7]
	s_min_u32 s6, s29, 0x71
	s_add_i32 s6, s27, s6
	s_lshl_b32 s6, s6, 2
	s_or_b32 s6, s6, s13
	s_waitcnt lgkmcnt(4)
	v_mfma_f32_32x32x16_bf16 v[16:31], v[20:23], v[28:31], 0
	v_add_u32_e32 v146, 9, v201
	v_min_u32_e32 v146, 0x7f, v146
	v_lshl_add_u32 v146, v146, 17, v128
	v_add_u32_e32 v147, 0x1000, v146
	s_waitcnt vmcnt(43)
	s_waitcnt lgkmcnt(3)
	v_mfma_f32_32x32x16_bf16 v[0:15], v[172:175], v[52:55], v[0:15]
	global_load_dwordx4 v[172:175], v146, s[100:101] offset:2048
	s_waitcnt vmcnt(43)
	s_waitcnt lgkmcnt(2)
	v_mfma_f32_32x32x16_bf16 v[16:31], v[176:179], v[138:141], v[16:31]
	global_load_dwordx4 v[176:179], v146, s[100:101] offset:3072
	ds_read_b128 v[52:55], v115 offset:14336
	ds_read_b128 v[138:141], v115 offset:15360
	s_waitcnt vmcnt(43)
	s_waitcnt lgkmcnt(3)
	v_mfma_f32_32x32x16_bf16 v[0:15], v[180:183], v[252:255], v[0:15]
	global_load_dwordx4 v[180:183], v147, s[100:101]
	v_lshl_add_u64 v[48:49], s[92:93], 0, v[100:101]
	v_add_co_u32_e32 v142, vcc, s28, v48
	v_lshl_add_u64 v[100:101], v[100:101], 0, s[8:9]
	s_nop 0
	v_addc_co_u32_e32 v143, vcc, 0, v49, vcc
	s_waitcnt vmcnt(43)
	s_waitcnt lgkmcnt(2)
	v_mfma_f32_32x32x16_bf16 v[16:31], v[184:187], v[202:205], v[16:31]
	global_load_dwordx4 v[184:187], v147, s[100:101] offset:1024
	s_waitcnt vmcnt(43)
	s_waitcnt lgkmcnt(1)
	v_mfma_f32_32x32x16_bf16 v[0:15], v[188:191], v[52:55], v[0:15]
	global_load_dwordx4 v[188:191], v147, s[100:101] offset:2048
	v_mov_b32_e32 v48, s30
	s_lshl_b32 s30, s6, 2
	s_lshl_b32 s6, s6, 15
	s_add_u32 s10, s10, 0x80
	s_addc_u32 s11, s11, 0
	s_cmpk_gt_u32 s29, 0x77
	s_waitcnt vmcnt(43)
	s_waitcnt lgkmcnt(0)
	v_mfma_f32_32x32x16_bf16 v[16:31], v[192:195], v[138:141], v[16:31]
	global_load_dwordx4 v[192:195], v147, s[100:101] offset:3072
	s_nop 11
	v_pk_add_f32 v[134:135], v[6:7], v[22:23]
	v_pk_add_f32 v[136:137], v[4:5], v[20:21]
	v_pk_add_f32 v[138:139], v[2:3], v[18:19]
	v_pk_add_f32 v[140:141], v[0:1], v[16:17]
	v_pk_add_f32 v[14:15], v[14:15], v[30:31]
	v_pk_add_f32 v[12:13], v[12:13], v[28:29]
	v_pk_add_f32 v[10:11], v[10:11], v[26:27]
	v_pk_add_f32 v[8:9], v[8:9], v[24:25]
	v_cvt_pk_bf16_f32 v0, v140, v141
	v_cvt_pk_bf16_f32 v1, v138, v139
	v_cvt_pk_bf16_f32 v2, v136, v137
	v_cvt_pk_bf16_f32 v3, v134, v135
	v_cvt_pk_bf16_f32 v4, v8, v9
	v_cvt_pk_bf16_f32 v5, v10, v11
	v_cvt_pk_bf16_f32 v6, v12, v13
	v_cvt_pk_bf16_f32 v7, v14, v15
	ds_write_b128 v119, v[0:3]
	ds_write_b128 v119, v[4:7] offset:1024
	global_store_dwordx4 v[142:143], v[0:3], off
	global_store_dwordx4 v[142:143], v[4:7], off offset:1024
	s_waitcnt lgkmcnt(0)
	s_barrier
	global_load_dword v118, v48, s[4:5]
	global_load_dwordx4 v[52:55], v[144:145], off
	s_nop 0
	global_load_dwordx4 v[48:51], v[144:145], off offset:1024
	ds_read_b128 v[16:19], v125
	ds_read_b128 v[20:23], v125 offset:1024
	ds_read_b128 v[24:27], v115
	ds_read_b128 v[28:31], v115 offset:1024
	v_lshlrev_b32_e32 v0, 16, v72
	v_and_b32_e32 v1, 0xffff0000, v72
	v_lshlrev_b32_e32 v2, 16, v73
	v_and_b32_e32 v3, 0xffff0000, v73
	v_lshlrev_b32_e32 v4, 16, v74
	v_and_b32_e32 v5, 0xffff0000, v74
	v_lshlrev_b32_e32 v6, 16, v75
	v_and_b32_e32 v7, 0xffff0000, v75
	v_lshlrev_b32_e32 v72, 16, v64
	v_and_b32_e32 v73, 0xffff0000, v64
	v_lshlrev_b32_e32 v64, 16, v65
	v_and_b32_e32 v65, 0xffff0000, v65
	v_lshlrev_b32_e32 v74, 16, v66
	v_and_b32_e32 v75, 0xffff0000, v66
	v_lshlrev_b32_e32 v66, 16, v67
	v_and_b32_e32 v67, 0xffff0000, v67
	v_pk_fma_f32 v[0:1], v[140:141], v[120:121], v[0:1] op_sel_hi:[1,0,1]
	v_pk_fma_f32 v[2:3], v[138:139], v[120:121], v[2:3] op_sel_hi:[1,0,1]
	v_pk_fma_f32 v[4:5], v[136:137], v[120:121], v[4:5] op_sel_hi:[1,0,1]
	v_pk_fma_f32 v[6:7], v[134:135], v[120:121], v[6:7] op_sel_hi:[1,0,1]
	v_pk_fma_f32 v[8:9], v[8:9], v[120:121], v[72:73] op_sel_hi:[1,0,1]
	v_pk_fma_f32 v[10:11], v[10:11], v[120:121], v[64:65] op_sel_hi:[1,0,1]
	v_pk_fma_f32 v[12:13], v[12:13], v[120:121], v[74:75] op_sel_hi:[1,0,1]
	v_pk_fma_f32 v[14:15], v[14:15], v[120:121], v[66:67] op_sel_hi:[1,0,1]
	ds_read_b128 v[72:75], v115 offset:2048
	ds_read_b128 v[138:141], v115 offset:3072
	ds_read_b128 v[252:255], v115 offset:4096
	ds_read_b128 v[202:205], v115 offset:5120
	s_waitcnt lgkmcnt(5)
	v_mfma_f32_32x32x16_bf16 v[0:15], v[16:19], v[24:27], v[0:15]
	v_lshl_add_u64 v[142:143], v[96:97], 0, s[6:7]
	s_waitcnt lgkmcnt(4)
	v_mfma_f32_32x32x16_bf16 v[16:31], v[20:23], v[28:31], 0
	v_add_u32_e32 v146, 10, v201
	v_min_u32_e32 v146, 0x7f, v146
	v_lshl_add_u32 v146, v146, 17, v128
	v_add_u32_e32 v147, 0x1000, v146
	s_waitcnt vmcnt(43)
	s_waitcnt lgkmcnt(3)
	v_mfma_f32_32x32x16_bf16 v[0:15], v[196:199], v[72:75], v[0:15]
	global_load_dwordx4 v[196:199], v146, s[100:101] offset:2048
	s_waitcnt vmcnt(43)
	s_waitcnt lgkmcnt(2)
	v_mfma_f32_32x32x16_bf16 v[16:31], v[208:211], v[138:141], v[16:31]
	global_load_dwordx4 v[208:211], v146, s[100:101] offset:3072
	ds_read_b128 v[72:75], v115 offset:6144
	ds_read_b128 v[138:141], v115 offset:7168
	s_waitcnt vmcnt(43)
	s_waitcnt lgkmcnt(3)
	v_mfma_f32_32x32x16_bf16 v[0:15], v[212:215], v[252:255], v[0:15]
	global_load_dwordx4 v[212:215], v147, s[100:101]
	v_lshl_add_u64 v[64:65], s[92:93], 0, v[98:99]
	v_add_co_u32_e32 v120, vcc, s28, v64
	v_lshl_add_u64 v[98:99], v[98:99], 0, s[8:9]
	s_nop 0
	v_addc_co_u32_e32 v121, vcc, 0, v65, vcc
	s_waitcnt vmcnt(43)
	s_waitcnt lgkmcnt(2)
	v_mfma_f32_32x32x16_bf16 v[16:31], v[216:219], v[202:205], v[16:31]
	global_load_dwordx4 v[216:219], v147, s[100:101] offset:1024
	s_waitcnt vmcnt(43)
	s_waitcnt lgkmcnt(1)
	v_mfma_f32_32x32x16_bf16 v[0:15], v[220:223], v[72:75], v[0:15]
	global_load_dwordx4 v[220:223], v147, s[100:101] offset:2048
	v_mov_b32_e32 v64, s30
	s_mov_b32 s30, s29
	s_waitcnt vmcnt(43)
	s_waitcnt lgkmcnt(0)
	v_mfma_f32_32x32x16_bf16 v[16:31], v[224:227], v[138:141], v[16:31]
	global_load_dwordx4 v[224:227], v147, s[100:101] offset:3072
	s_nop 11
	v_pk_add_f32 v[134:135], v[6:7], v[22:23]
	v_pk_add_f32 v[136:137], v[4:5], v[20:21]
	v_pk_add_f32 v[138:139], v[2:3], v[18:19]
	v_pk_add_f32 v[140:141], v[0:1], v[16:17]
	v_pk_add_f32 v[14:15], v[14:15], v[30:31]
	v_pk_add_f32 v[12:13], v[12:13], v[28:29]
	v_pk_add_f32 v[10:11], v[10:11], v[26:27]
	v_pk_add_f32 v[8:9], v[8:9], v[24:25]
	v_cvt_pk_bf16_f32 v0, v140, v141
	v_cvt_pk_bf16_f32 v1, v138, v139
	v_cvt_pk_bf16_f32 v2, v136, v137
	v_cvt_pk_bf16_f32 v3, v134, v135
	v_cvt_pk_bf16_f32 v4, v8, v9
	v_cvt_pk_bf16_f32 v5, v10, v11
	v_cvt_pk_bf16_f32 v6, v12, v13
	v_cvt_pk_bf16_f32 v7, v14, v15
	ds_write_b128 v117, v[0:3] offset:8192
	ds_write_b128 v117, v[4:7] offset:9216
	global_store_dwordx4 v[120:121], v[0:3], off
	global_store_dwordx4 v[120:121], v[4:7], off offset:1024
	s_waitcnt lgkmcnt(0)
	s_barrier
; #define LAS __attribute__((address_space(3)))
; __device__ __forceinline__ int scan_item(int bh, int n) { if (n > NCH - 1) n = NCH - 1; return ((bh >> 2) * NCH + n) * 4 + (bh & 3); }
; __device__ __forceinline__ void scanb_load(ScanB& p, const unsigned char* ws, int bh, int n, int td, int te, int lane) {
;     const int item = scan_item(bh, n);
;     p.egl = ((const float*)(ws + WS_GL))[item];
;     const bf16* Bs = (const bf16*)(ws + WS_BS) + (size_t)item * 16384 + (te * 4 + td) * 1024 + lane * 8;
;     p.bn[0] = *(const v4u*)Bs; p.bn[1] = *(const v4u*)(Bs + 512);
; }
; __device__ __forceinline__ void scan_step(const ScanB& p, f32x16& acc, unsigned char* ws, LAS unsigned char* lds, int bh, int n, int cur, int td, int te, int lane) {
;     const int item = scan_item(bh, n);
;     v4u b0 = p.bn[0], b1 = p.bn[1]; float egl = p.egl;
;     asm volatile("" : "+v"(egl)); asm volatile("" : "+v"(b0)); asm volatile("" : "+v"(b1));
;     f32x16 bv16; ans_unpack(b0, b1, bv16);
; #pragma unroll
;     for (int r = 0; r < 16; ++r) acc[r] = acc[r] * egl + bv16[r];
;     const LAS unsigned char* sb = lds + cur * 8192 + lane * 16;
;     const LAS unsigned char* sa = lds + SC_RING + (n & 3) * SC_SLOT + td * 8192 + lane * 16;
;     f32x16 acc2 = zero16();
; #pragma unroll
;     for (int q = 0; q < 8; q += 2) {
;         const bf16x8 a0 = *(const LAS bf16x8*)(sa + 1024 * q), bv0 = *(const LAS bf16x8*)(sb + 1024 * q);
;         const bf16x8 a1 = *(const LAS bf16x8*)(sa + 1024 * (q + 1)), bv1 = *(const LAS bf16x8*)(sb + 1024 * (q + 1));
;         acc = __builtin_amdgcn_mfma_f32_32x32x16_bf16(a0, bv0, acc, 0, 0, 0); acc2 = __builtin_amdgcn_mfma_f32_32x32x16_bf16(a1, bv1, acc2, 0, 0, 0); }
; #pragma unroll
;     for (int r = 0; r < 16; ++r) acc[r] += acc2[r];
;     v4u w0, w1; ans_pack(acc, w0, w1);
;     LAS unsigned char* sn = lds + (cur ^ 1) * 8192 + td * 2048 + lane * 16;
;     *(LAS v4u*)sn = w0; *(LAS v4u*)(sn + 1024) = w1;
;     bf16* So = (bf16*)(ws + WS_BS) + (size_t)item * 16384 + (te * 4 + td) * 1024 + lane * 8;
;     *(v4u*)So = w0; *(v4u*)(So + 512) = w1;
	global_load_dword v120, v64, s[4:5]
	global_load_dwordx4 v[72:75], v[142:143], off
	s_nop 0
	global_load_dwordx4 v[64:67], v[142:143], off offset:1024
	ds_read_b128 v[16:19], v127
	ds_read_b128 v[20:23], v127 offset:1024
	ds_read_b128 v[24:27], v115 offset:8192
	ds_read_b128 v[28:31], v115 offset:9216
	v_lshlrev_b32_e32 v0, 16, v92
	v_and_b32_e32 v1, 0xffff0000, v92
	v_lshlrev_b32_e32 v2, 16, v93
	v_and_b32_e32 v3, 0xffff0000, v93
	v_lshlrev_b32_e32 v4, 16, v94
	v_and_b32_e32 v5, 0xffff0000, v94
	v_lshlrev_b32_e32 v6, 16, v95
	v_and_b32_e32 v7, 0xffff0000, v95
	v_lshlrev_b32_e32 v92, 16, v88
	v_and_b32_e32 v93, 0xffff0000, v88
	v_lshlrev_b32_e32 v88, 16, v89
	v_and_b32_e32 v89, 0xffff0000, v89
	v_lshlrev_b32_e32 v94, 16, v90
	v_and_b32_e32 v95, 0xffff0000, v90
	v_lshlrev_b32_e32 v90, 16, v91
	v_and_b32_e32 v91, 0xffff0000, v91
	v_pk_fma_f32 v[0:1], v[140:141], v[132:133], v[0:1] op_sel_hi:[1,0,1]
	v_pk_fma_f32 v[2:3], v[138:139], v[132:133], v[2:3] op_sel_hi:[1,0,1]
	v_pk_fma_f32 v[4:5], v[136:137], v[132:133], v[4:5] op_sel_hi:[1,0,1]
	v_pk_fma_f32 v[6:7], v[134:135], v[132:133], v[6:7] op_sel_hi:[1,0,1]
	v_pk_fma_f32 v[8:9], v[8:9], v[132:133], v[92:93] op_sel_hi:[1,0,1]
	v_pk_fma_f32 v[10:11], v[10:11], v[132:133], v[88:89] op_sel_hi:[1,0,1]
	v_pk_fma_f32 v[12:13], v[12:13], v[132:133], v[94:95] op_sel_hi:[1,0,1]
	v_pk_fma_f32 v[14:15], v[14:15], v[132:133], v[90:91] op_sel_hi:[1,0,1]
	ds_read_b128 v[92:95], v115 offset:10240
	ds_read_b128 v[136:139], v115 offset:11264
	ds_read_b128 v[252:255], v115 offset:12288
	ds_read_b128 v[202:205], v115 offset:13312
	s_waitcnt lgkmcnt(5)
	v_mfma_f32_32x32x16_bf16 v[0:15], v[16:19], v[24:27], v[0:15]
	s_waitcnt lgkmcnt(4)
	v_mfma_f32_32x32x16_bf16 v[16:31], v[20:23], v[28:31], 0
	v_add_u32_e32 v146, 11, v201
	v_min_u32_e32 v146, 0x7f, v146
	v_lshl_add_u32 v146, v146, 17, v128
	v_add_u32_e32 v147, 0x1000, v146
	s_waitcnt vmcnt(43)
	s_waitcnt lgkmcnt(3)
	v_mfma_f32_32x32x16_bf16 v[0:15], v[228:231], v[92:95], v[0:15]
	global_load_dwordx4 v[228:231], v146, s[100:101] offset:2048
	s_waitcnt vmcnt(43)
	s_waitcnt lgkmcnt(2)
	v_mfma_f32_32x32x16_bf16 v[16:31], v[232:235], v[136:139], v[16:31]
	global_load_dwordx4 v[232:235], v146, s[100:101] offset:3072
	ds_read_b128 v[92:95], v115 offset:14336
	ds_read_b128 v[136:139], v115 offset:15360
	s_waitcnt vmcnt(43)
	s_waitcnt lgkmcnt(3)
	v_mfma_f32_32x32x16_bf16 v[0:15], v[236:239], v[252:255], v[0:15]
	global_load_dwordx4 v[236:239], v147, s[100:101]
	s_waitcnt vmcnt(43)
	s_waitcnt lgkmcnt(2)
	v_mfma_f32_32x32x16_bf16 v[16:31], v[240:243], v[202:205], v[16:31]
	global_load_dwordx4 v[240:243], v147, s[100:101] offset:1024
	s_waitcnt vmcnt(43)
	s_waitcnt lgkmcnt(1)
	v_mfma_f32_32x32x16_bf16 v[0:15], v[244:247], v[92:95], v[0:15]
	global_load_dwordx4 v[244:247], v147, s[100:101] offset:2048
	s_waitcnt vmcnt(43)
	s_waitcnt lgkmcnt(0)
	v_mfma_f32_32x32x16_bf16 v[16:31], v[248:251], v[136:139], v[16:31]
	global_load_dwordx4 v[248:251], v147, s[100:101] offset:3072
	s_nop 11
	v_pk_add_f32 v[6:7], v[6:7], v[22:23]
	v_pk_add_f32 v[4:5], v[4:5], v[20:21]
	v_pk_add_f32 v[2:3], v[2:3], v[18:19]
	v_pk_add_f32 v[0:1], v[0:1], v[16:17]
	v_pk_add_f32 v[14:15], v[14:15], v[30:31]
	v_pk_add_f32 v[12:13], v[12:13], v[28:29]
	v_pk_add_f32 v[10:11], v[10:11], v[26:27]
	v_pk_add_f32 v[8:9], v[8:9], v[24:25]
	v_cvt_pk_bf16_f32 v16, v0, v1
	v_cvt_pk_bf16_f32 v17, v2, v3
	v_cvt_pk_bf16_f32 v18, v4, v5
	v_cvt_pk_bf16_f32 v19, v6, v7
	v_cvt_pk_bf16_f32 v20, v8, v9
	v_cvt_pk_bf16_f32 v21, v10, v11
	v_cvt_pk_bf16_f32 v22, v12, v13
	v_cvt_pk_bf16_f32 v23, v14, v15
	ds_write_b128 v119, v[16:19]
	ds_write_b128 v119, v[20:23] offset:1024
	global_store_dwordx4 v[130:131], v[16:19], off
	global_store_dwordx4 v[130:131], v[20:23], off offset:1024
	s_waitcnt lgkmcnt(0)
	s_barrier
	s_cbranch_scc0 .LBB0_1068
